# kraw_items (implicit-filter taps, f32 GEMM 12288x64x1536) moved from VALU readlane+fmac to f32 matrix cores v_mfma_f32_32x32x2_f32 (f32 in, f32 accumulate); plus wide pipelined row prep, P3 wait fix,
# speedup vs baseline: 1.0219x; 1.0073x over previous
; __device__ __forceinline__ void kraw_items(const Args& a, int gw, int NGW, int lane) {
;     const float* H3 = (const float*)(a.ws + WS_H3); float* KR = (float*)(a.ws + WS_KRAW);
;     for (int it = gw; it < 192 * 32; it += NGW) {
;         const int pg = it >> 5, cgp = it & 31, p = pg * 64 + lane, c0 = cgp * 48;
;         float h[64];
; #pragma unroll
;         for (int q = 0; q < 16; ++q) { const f32x4 t = *(const f32x4*)(H3 + (size_t)p * 64 + 4 * q); h[4 * q] = t.x; h[4 * q + 1] = t.y; h[4 * q + 2] = t.z; h[4 * q + 3] = t.w; }
;         const int grp = p >= LP, tpos = p - grp * LP, L = grp ? LS : LP;
;         const float tt = (float)tpos * (1.0f / (float)(L - 1));
; #pragma unroll 1
;         for (int cb = 0; cb < 4; ++cb) {
;             const float* wr = a.in[I_FWOUT] + lane * 1536 + c0 + 12 * cb;
;             const f32x4 w0 = *(const f32x4*)(wr), w1 = *(const f32x4*)(wr + 4), w2 = *(const f32x4*)(wr + 8);
;             float wv[12] = {w0.x, w0.y, w0.z, w0.w, w1.x, w1.y, w1.z, w1.w, w2.x, w2.y, w2.z, w2.w};
.LBB0_116:
	s_load_dwordx2 s[6:7], s[72:73], 0x90
	s_load_dwordx2 s[8:9], s[72:73], 0xe8
	v_and_b32_e32 v119, 63, v254
	v_and_b32_e32 v112, 31, v119
	v_lshrrev_b32_e32 v113, 5, v119
	v_lshlrev_b32_e32 v114, 8, v112
	v_lshl_add_u32 v114, v113, 7, v114
	v_mul_u32_u24_e32 v115, 0x30000, v113
	v_lshl_add_u32 v115, v112, 2, v115
	v_lshlrev_b32_e32 v118, 2, v113
	v_readfirstlane_b32 s16, v254
	s_nop 3
	s_lshl_b32 s30, s96, 3
	s_lshr_b32 s16, s16, 6
	s_add_i32 s16, s16, s30
	v_mov_b32_e32 v120, 0xc0447cbd
	s_waitcnt lgkmcnt(0)
	s_add_u32 s10, s8, 0x100000
	s_addc_u32 s11, s9, 0
	s_add_u32 s14, s8, 0x37000000
	s_addc_u32 s15, s9, 0
	s_mov_b32 s17, s16
	s_lshr_b32 s18, s17, 4
	s_and_b32 s19, s17, 15
	s_lshl_b32 s20, s18, 5
	s_mul_i32 s21, s19, 0x60
	s_lshl_b32 s30, s20, 8
	s_add_u32 s24, s10, s30
	s_addc_u32 s25, s11, 0
	global_load_dwordx4 v[0:3], v114, s[24:25] offset:0
	global_load_dwordx4 v[4:7], v114, s[24:25] offset:16
	global_load_dwordx4 v[8:11], v114, s[24:25] offset:32
	global_load_dwordx4 v[12:15], v114, s[24:25] offset:48
	global_load_dwordx4 v[16:19], v114, s[24:25] offset:64
	global_load_dwordx4 v[20:23], v114, s[24:25] offset:80
	global_load_dwordx4 v[24:27], v114, s[24:25] offset:96
	global_load_dwordx4 v[28:31], v114, s[24:25] offset:112
	s_add_i32 s30, s21, 0
	s_lshl_b32 s30, s30, 2
	s_add_u32 s26, s6, s30
	s_addc_u32 s27, s7, 0
	global_load_dword v64, v115, s[26:27]
	s_add_u32 s26, s26, 0x1800
	s_addc_u32 s27, s27, 0
	global_load_dword v65, v115, s[26:27]
	s_add_u32 s26, s26, 0x1800
	s_addc_u32 s27, s27, 0
	global_load_dword v66, v115, s[26:27]
	s_add_u32 s26, s26, 0x1800
	s_addc_u32 s27, s27, 0
	global_load_dword v67, v115, s[26:27]
	s_add_u32 s26, s26, 0x1800
	s_addc_u32 s27, s27, 0
	global_load_dword v68, v115, s[26:27]
	s_add_u32 s26, s26, 0x1800
	s_addc_u32 s27, s27, 0
	global_load_dword v69, v115, s[26:27]
	s_add_u32 s26, s26, 0x1800
	s_addc_u32 s27, s27, 0
	global_load_dword v70, v115, s[26:27]
	s_add_u32 s26, s26, 0x1800
	s_addc_u32 s27, s27, 0
	global_load_dword v71, v115, s[26:27]
	s_add_u32 s26, s26, 0x1800
	s_addc_u32 s27, s27, 0
	global_load_dword v72, v115, s[26:27]
	s_add_u32 s26, s26, 0x1800
	s_addc_u32 s27, s27, 0
	global_load_dword v73, v115, s[26:27]
	s_add_u32 s26, s26, 0x1800
	s_addc_u32 s27, s27, 0
	global_load_dword v74, v115, s[26:27]
	s_add_u32 s26, s26, 0x1800
	s_addc_u32 s27, s27, 0
	global_load_dword v75, v115, s[26:27]
	s_add_u32 s26, s26, 0x1800
	s_addc_u32 s27, s27, 0
	global_load_dword v76, v115, s[26:27]
	s_add_u32 s26, s26, 0x1800
	s_addc_u32 s27, s27, 0
	global_load_dword v77, v115, s[26:27]
	s_add_u32 s26, s26, 0x1800
	s_addc_u32 s27, s27, 0
	global_load_dword v78, v115, s[26:27]
	s_add_u32 s26, s26, 0x1800
	s_addc_u32 s27, s27, 0
	global_load_dword v79, v115, s[26:27]
	s_add_u32 s26, s26, 0x1800
	s_addc_u32 s27, s27, 0
	global_load_dword v80, v115, s[26:27]
	s_add_u32 s26, s26, 0x1800
	s_addc_u32 s27, s27, 0
	global_load_dword v81, v115, s[26:27]
	s_add_u32 s26, s26, 0x1800
	s_addc_u32 s27, s27, 0
	global_load_dword v82, v115, s[26:27]
	s_add_u32 s26, s26, 0x1800
	s_addc_u32 s27, s27, 0
	global_load_dword v83, v115, s[26:27]
	s_add_u32 s26, s26, 0x1800
	s_addc_u32 s27, s27, 0
	global_load_dword v84, v115, s[26:27]
	s_add_u32 s26, s26, 0x1800
	s_addc_u32 s27, s27, 0
	global_load_dword v85, v115, s[26:27]
	s_add_u32 s26, s26, 0x1800
	s_addc_u32 s27, s27, 0
	global_load_dword v86, v115, s[26:27]
	s_add_u32 s26, s26, 0x1800
	s_addc_u32 s27, s27, 0
	global_load_dword v87, v115, s[26:27]
	s_add_u32 s26, s26, 0x1800
	s_addc_u32 s27, s27, 0
	global_load_dword v88, v115, s[26:27]
	s_add_u32 s26, s26, 0x1800
	s_addc_u32 s27, s27, 0
	global_load_dword v89, v115, s[26:27]
	s_add_u32 s26, s26, 0x1800
	s_addc_u32 s27, s27, 0
	global_load_dword v90, v115, s[26:27]
	s_add_u32 s26, s26, 0x1800
	s_addc_u32 s27, s27, 0
	global_load_dword v91, v115, s[26:27]
	s_add_u32 s26, s26, 0x1800
	s_addc_u32 s27, s27, 0
	global_load_dword v92, v115, s[26:27]
	s_add_u32 s26, s26, 0x1800
	s_addc_u32 s27, s27, 0
	global_load_dword v93, v115, s[26:27]
	s_add_u32 s26, s26, 0x1800
	s_addc_u32 s27, s27, 0
	global_load_dword v94, v115, s[26:27]
	s_add_u32 s26, s26, 0x1800
	s_addc_u32 s27, s27, 0
	global_load_dword v95, v115, s[26:27]
	s_add_i32 s28, s21, 0
	s_sub_i32 s29, s28, 0x300
	s_cmp_ge_u32 s28, 0x300
	s_cselect_b32 s29, s29, s28
	s_mul_i32 s30, s28, 0xc000
	s_lshl_b32 s35, s20, 2
	s_add_u32 s30, s30, s35
	s_add_u32 s34, s14, s30
	s_addc_u32 s35, s15, 0
	s_mov_b32 s22, 0xb9000400
	s_cmp_ge_u32 s20, 0x2000
	s_cselect_b32 s22, 0xb9800801, s22
	s_and_b32 s30, s20, 0x1fff
	v_add_u32_e32 v119, s30, v112
	v_cvt_f32_u32_e32 v119, v119
	v_mul_f32_e32 v117, s22, v119
	s_add_i32 s30, s21, 32
	s_lshl_b32 s30, s30, 2
	s_add_u32 s26, s6, s30
	s_addc_u32 s27, s7, 0
	global_load_dword v128, v115, s[26:27]
	s_add_u32 s26, s26, 0x1800
	s_addc_u32 s27, s27, 0
	global_load_dword v129, v115, s[26:27]
	s_add_u32 s26, s26, 0x1800
	s_addc_u32 s27, s27, 0
	global_load_dword v130, v115, s[26:27]
	s_add_u32 s26, s26, 0x1800
	s_addc_u32 s27, s27, 0
	global_load_dword v131, v115, s[26:27]
	s_add_u32 s26, s26, 0x1800
	s_addc_u32 s27, s27, 0
	global_load_dword v132, v115, s[26:27]
	s_add_u32 s26, s26, 0x1800
	s_addc_u32 s27, s27, 0
	global_load_dword v133, v115, s[26:27]
	s_add_u32 s26, s26, 0x1800
	s_addc_u32 s27, s27, 0
	global_load_dword v134, v115, s[26:27]
	s_add_u32 s26, s26, 0x1800
	s_addc_u32 s27, s27, 0
	global_load_dword v135, v115, s[26:27]
	s_add_u32 s26, s26, 0x1800
	s_addc_u32 s27, s27, 0
	global_load_dword v136, v115, s[26:27]
	s_add_u32 s26, s26, 0x1800
	s_addc_u32 s27, s27, 0
	global_load_dword v137, v115, s[26:27]
	s_add_u32 s26, s26, 0x1800
; __device__ __forceinline__ void kraw_items(const Args& a, int gw, int NGW, int lane) {
;     ...
;             const float* wr = a.in[I_FWOUT] + lane * 1536 + c0 + 12 * cb;
;             const f32x4 w0 = *(const f32x4*)(wr), w1 = *(const f32x4*)(wr + 4), w2 = *(const f32x4*)(wr + 8);
;             float wv[12] = {w0.x, w0.y, w0.z, w0.w, w1.x, w1.y, w1.z, w1.w, w2.x, w2.y, w2.z, w2.w};
; #pragma unroll
;             for (int ci = 0; ci < 12; ++ci) { const int c = c0 + 12 * cb + ci;
;                 float acc = 0.f;
; #pragma unroll
;                 for (int jj = 0; jj < 64; ++jj) acc += h[jj] * __builtin_bit_cast(float, __builtin_amdgcn_readlane(__builtin_bit_cast(int, wv[ci]), jj));
;                 const int cm = c % 768;
;                 const float delta = fabsf(-3.0701134573253945f + (float)cm * ((-15.350567286626973f + 3.0701134573253945f) / 767.0f));
;                 KR[(size_t)c * (LP + LS) + p] = acc * __expf(-tt * delta); }
	s_addc_u32 s27, s27, 0
	global_load_dword v138, v115, s[26:27]
	s_add_u32 s26, s26, 0x1800
	s_addc_u32 s27, s27, 0
	global_load_dword v139, v115, s[26:27]
	s_add_u32 s26, s26, 0x1800
	s_addc_u32 s27, s27, 0
	global_load_dword v140, v115, s[26:27]
	s_add_u32 s26, s26, 0x1800
	s_addc_u32 s27, s27, 0
	global_load_dword v141, v115, s[26:27]
	s_add_u32 s26, s26, 0x1800
	s_addc_u32 s27, s27, 0
	global_load_dword v142, v115, s[26:27]
	s_add_u32 s26, s26, 0x1800
	s_addc_u32 s27, s27, 0
	global_load_dword v143, v115, s[26:27]
	s_add_u32 s26, s26, 0x1800
	s_addc_u32 s27, s27, 0
	global_load_dword v144, v115, s[26:27]
	s_add_u32 s26, s26, 0x1800
	s_addc_u32 s27, s27, 0
	global_load_dword v145, v115, s[26:27]
	s_add_u32 s26, s26, 0x1800
	s_addc_u32 s27, s27, 0
	global_load_dword v146, v115, s[26:27]
	s_add_u32 s26, s26, 0x1800
	s_addc_u32 s27, s27, 0
	global_load_dword v147, v115, s[26:27]
	s_add_u32 s26, s26, 0x1800
	s_addc_u32 s27, s27, 0
	global_load_dword v148, v115, s[26:27]
	s_add_u32 s26, s26, 0x1800
	s_addc_u32 s27, s27, 0
	global_load_dword v149, v115, s[26:27]
	s_add_u32 s26, s26, 0x1800
	s_addc_u32 s27, s27, 0
	global_load_dword v150, v115, s[26:27]
	s_add_u32 s26, s26, 0x1800
	s_addc_u32 s27, s27, 0
	global_load_dword v151, v115, s[26:27]
	s_add_u32 s26, s26, 0x1800
	s_addc_u32 s27, s27, 0
	global_load_dword v152, v115, s[26:27]
	s_add_u32 s26, s26, 0x1800
	s_addc_u32 s27, s27, 0
	global_load_dword v153, v115, s[26:27]
	s_add_u32 s26, s26, 0x1800
	s_addc_u32 s27, s27, 0
	global_load_dword v154, v115, s[26:27]
	s_add_u32 s26, s26, 0x1800
	s_addc_u32 s27, s27, 0
	global_load_dword v155, v115, s[26:27]
	s_add_u32 s26, s26, 0x1800
	s_addc_u32 s27, s27, 0
	global_load_dword v156, v115, s[26:27]
	s_add_u32 s26, s26, 0x1800
	s_addc_u32 s27, s27, 0
	global_load_dword v157, v115, s[26:27]
	s_add_u32 s26, s26, 0x1800
	s_addc_u32 s27, s27, 0
	global_load_dword v158, v115, s[26:27]
	s_add_u32 s26, s26, 0x1800
	s_addc_u32 s27, s27, 0
	global_load_dword v159, v115, s[26:27]
	s_waitcnt vmcnt(32)
	v_mfma_f32_32x32x2_f32 v[96:111], v64, v0, 0
	v_mfma_f32_32x32x2_f32 v[96:111], v65, v1, v[96:111]
	v_mfma_f32_32x32x2_f32 v[96:111], v66, v2, v[96:111]
	v_mfma_f32_32x32x2_f32 v[96:111], v67, v3, v[96:111]
	v_mfma_f32_32x32x2_f32 v[96:111], v68, v4, v[96:111]
	v_mfma_f32_32x32x2_f32 v[96:111], v69, v5, v[96:111]
	v_mfma_f32_32x32x2_f32 v[96:111], v70, v6, v[96:111]
	v_mfma_f32_32x32x2_f32 v[96:111], v71, v7, v[96:111]
	v_mfma_f32_32x32x2_f32 v[96:111], v72, v8, v[96:111]
	v_mfma_f32_32x32x2_f32 v[96:111], v73, v9, v[96:111]
	v_mfma_f32_32x32x2_f32 v[96:111], v74, v10, v[96:111]
	v_mfma_f32_32x32x2_f32 v[96:111], v75, v11, v[96:111]
	v_mfma_f32_32x32x2_f32 v[96:111], v76, v12, v[96:111]
	v_mfma_f32_32x32x2_f32 v[96:111], v77, v13, v[96:111]
	v_mfma_f32_32x32x2_f32 v[96:111], v78, v14, v[96:111]
	v_mfma_f32_32x32x2_f32 v[96:111], v79, v15, v[96:111]
	v_mfma_f32_32x32x2_f32 v[96:111], v80, v16, v[96:111]
	v_mfma_f32_32x32x2_f32 v[96:111], v81, v17, v[96:111]
	v_mfma_f32_32x32x2_f32 v[96:111], v82, v18, v[96:111]
	v_mfma_f32_32x32x2_f32 v[96:111], v83, v19, v[96:111]
	v_mfma_f32_32x32x2_f32 v[96:111], v84, v20, v[96:111]
	v_mfma_f32_32x32x2_f32 v[96:111], v85, v21, v[96:111]
	v_mfma_f32_32x32x2_f32 v[96:111], v86, v22, v[96:111]
	v_mfma_f32_32x32x2_f32 v[96:111], v87, v23, v[96:111]
	v_mfma_f32_32x32x2_f32 v[96:111], v88, v24, v[96:111]
	v_mfma_f32_32x32x2_f32 v[96:111], v89, v25, v[96:111]
	v_mfma_f32_32x32x2_f32 v[96:111], v90, v26, v[96:111]
	v_mfma_f32_32x32x2_f32 v[96:111], v91, v27, v[96:111]
	v_mfma_f32_32x32x2_f32 v[96:111], v92, v28, v[96:111]
	v_mfma_f32_32x32x2_f32 v[96:111], v93, v29, v[96:111]
	v_mfma_f32_32x32x2_f32 v[96:111], v94, v30, v[96:111]
	v_mfma_f32_32x32x2_f32 v[96:111], v95, v31, v[96:111]
	s_add_i32 s30, s29, 0
	v_add_u32_e32 v119, s30, v118
	v_cvt_f32_u32_e32 v119, v119
	v_fmamk_f32 v119, v119, 0xbc83298c, v120
	v_mul_f32_e64 v119, v117, |v119|
	v_mul_f32_e32 v119, 0x3fb8aa3b, v119
	v_exp_f32_e32 v160, v119
	s_add_i32 s30, s29, 1
	v_add_u32_e32 v119, s30, v118
	v_cvt_f32_u32_e32 v119, v119
	v_fmamk_f32 v119, v119, 0xbc83298c, v120
	v_mul_f32_e64 v119, v117, |v119|
	v_mul_f32_e32 v119, 0x3fb8aa3b, v119
	v_exp_f32_e32 v161, v119
	s_add_i32 s30, s29, 2
	v_add_u32_e32 v119, s30, v118
	v_cvt_f32_u32_e32 v119, v119
	v_fmamk_f32 v119, v119, 0xbc83298c, v120
	v_mul_f32_e64 v119, v117, |v119|
	v_mul_f32_e32 v119, 0x3fb8aa3b, v119
	v_exp_f32_e32 v162, v119
	s_add_i32 s30, s29, 3
	v_add_u32_e32 v119, s30, v118
	v_cvt_f32_u32_e32 v119, v119
	v_fmamk_f32 v119, v119, 0xbc83298c, v120
	v_mul_f32_e64 v119, v117, |v119|
	v_mul_f32_e32 v119, 0x3fb8aa3b, v119
	v_exp_f32_e32 v163, v119
	s_add_i32 s30, s29, 8
	v_add_u32_e32 v119, s30, v118
	v_cvt_f32_u32_e32 v119, v119
	v_fmamk_f32 v119, v119, 0xbc83298c, v120
	v_mul_f32_e64 v119, v117, |v119|
	v_mul_f32_e32 v119, 0x3fb8aa3b, v119
	v_exp_f32_e32 v164, v119
	s_add_i32 s30, s29, 9
	v_add_u32_e32 v119, s30, v118
	v_cvt_f32_u32_e32 v119, v119
	v_fmamk_f32 v119, v119, 0xbc83298c, v120
	v_mul_f32_e64 v119, v117, |v119|
	v_mul_f32_e32 v119, 0x3fb8aa3b, v119
	v_exp_f32_e32 v165, v119
	s_add_i32 s30, s29, 10
	v_add_u32_e32 v119, s30, v118
	v_cvt_f32_u32_e32 v119, v119
	v_fmamk_f32 v119, v119, 0xbc83298c, v120
	v_mul_f32_e64 v119, v117, |v119|
	v_mul_f32_e32 v119, 0x3fb8aa3b, v119
	v_exp_f32_e32 v166, v119
	s_add_i32 s30, s29, 11
	v_add_u32_e32 v119, s30, v118
	v_cvt_f32_u32_e32 v119, v119
	v_fmamk_f32 v119, v119, 0xbc83298c, v120
	v_mul_f32_e64 v119, v117, |v119|
	v_mul_f32_e32 v119, 0x3fb8aa3b, v119
	v_exp_f32_e32 v167, v119
	s_add_i32 s30, s29, 16
	v_add_u32_e32 v119, s30, v118
	v_cvt_f32_u32_e32 v119, v119
; __device__ __forceinline__ void kraw_items(const Args& a, int gw, int NGW, int lane) {
;     ...
;             const float* wr = a.in[I_FWOUT] + lane * 1536 + c0 + 12 * cb;
;             const f32x4 w0 = *(const f32x4*)(wr), w1 = *(const f32x4*)(wr + 4), w2 = *(const f32x4*)(wr + 8);
;             float wv[12] = {w0.x, w0.y, w0.z, w0.w, w1.x, w1.y, w1.z, w1.w, w2.x, w2.y, w2.z, w2.w};
; #pragma unroll
;             for (int ci = 0; ci < 12; ++ci) { const int c = c0 + 12 * cb + ci;
;                 float acc = 0.f;
; #pragma unroll
;                 for (int jj = 0; jj < 64; ++jj) acc += h[jj] * __builtin_bit_cast(float, __builtin_amdgcn_readlane(__builtin_bit_cast(int, wv[ci]), jj));
;                 const int cm = c % 768;
;                 const float delta = fabsf(-3.0701134573253945f + (float)cm * ((-15.350567286626973f + 3.0701134573253945f) / 767.0f));
;                 KR[(size_t)c * (LP + LS) + p] = acc * __expf(-tt * delta); }
	v_fmamk_f32 v119, v119, 0xbc83298c, v120
	v_mul_f32_e64 v119, v117, |v119|
	v_mul_f32_e32 v119, 0x3fb8aa3b, v119
	v_exp_f32_e32 v168, v119
	s_add_i32 s30, s29, 17
	v_add_u32_e32 v119, s30, v118
	v_cvt_f32_u32_e32 v119, v119
	v_fmamk_f32 v119, v119, 0xbc83298c, v120
	v_mul_f32_e64 v119, v117, |v119|
	v_mul_f32_e32 v119, 0x3fb8aa3b, v119
	v_exp_f32_e32 v169, v119
	s_add_i32 s30, s29, 18
	v_add_u32_e32 v119, s30, v118
	v_cvt_f32_u32_e32 v119, v119
	v_fmamk_f32 v119, v119, 0xbc83298c, v120
	v_mul_f32_e64 v119, v117, |v119|
	v_mul_f32_e32 v119, 0x3fb8aa3b, v119
	v_exp_f32_e32 v170, v119
	s_add_i32 s30, s29, 19
	v_add_u32_e32 v119, s30, v118
	v_cvt_f32_u32_e32 v119, v119
	v_fmamk_f32 v119, v119, 0xbc83298c, v120
	v_mul_f32_e64 v119, v117, |v119|
	v_mul_f32_e32 v119, 0x3fb8aa3b, v119
	v_exp_f32_e32 v171, v119
	s_add_i32 s30, s29, 24
	v_add_u32_e32 v119, s30, v118
	v_cvt_f32_u32_e32 v119, v119
	v_fmamk_f32 v119, v119, 0xbc83298c, v120
	v_mul_f32_e64 v119, v117, |v119|
	v_mul_f32_e32 v119, 0x3fb8aa3b, v119
	v_exp_f32_e32 v172, v119
	s_add_i32 s30, s29, 25
	v_add_u32_e32 v119, s30, v118
	v_cvt_f32_u32_e32 v119, v119
	v_fmamk_f32 v119, v119, 0xbc83298c, v120
	v_mul_f32_e64 v119, v117, |v119|
	v_mul_f32_e32 v119, 0x3fb8aa3b, v119
	v_exp_f32_e32 v173, v119
	s_add_i32 s30, s29, 26
	v_add_u32_e32 v119, s30, v118
	v_cvt_f32_u32_e32 v119, v119
	v_fmamk_f32 v119, v119, 0xbc83298c, v120
	v_mul_f32_e64 v119, v117, |v119|
	v_mul_f32_e32 v119, 0x3fb8aa3b, v119
	v_exp_f32_e32 v174, v119
	s_add_i32 s30, s29, 27
	v_add_u32_e32 v119, s30, v118
	v_cvt_f32_u32_e32 v119, v119
	v_fmamk_f32 v119, v119, 0xbc83298c, v120
	v_mul_f32_e64 v119, v117, |v119|
	v_mul_f32_e32 v119, 0x3fb8aa3b, v119
	v_exp_f32_e32 v175, v119
	s_nop 7
	v_mul_f32_e32 v176, v96, v160
	s_mov_b64 s[36:37], s[34:35]
	global_store_dword v115, v176, s[36:37]
	v_mul_f32_e32 v177, v97, v161
	s_add_u32 s36, s34, 0xc000
	s_addc_u32 s37, s35, 0
	global_store_dword v115, v177, s[36:37]
	v_mul_f32_e32 v178, v98, v162
	s_add_u32 s36, s34, 0x18000
	s_addc_u32 s37, s35, 0
	global_store_dword v115, v178, s[36:37]
	v_mul_f32_e32 v179, v99, v163
	s_add_u32 s36, s34, 0x24000
	s_addc_u32 s37, s35, 0
	global_store_dword v115, v179, s[36:37]
	v_mul_f32_e32 v180, v100, v164
	s_add_u32 s36, s34, 0x60000
	s_addc_u32 s37, s35, 0
	global_store_dword v115, v180, s[36:37]
	v_mul_f32_e32 v181, v101, v165
	s_add_u32 s36, s34, 0x6c000
	s_addc_u32 s37, s35, 0
	global_store_dword v115, v181, s[36:37]
	v_mul_f32_e32 v182, v102, v166
	s_add_u32 s36, s34, 0x78000
	s_addc_u32 s37, s35, 0
	global_store_dword v115, v182, s[36:37]
	v_mul_f32_e32 v183, v103, v167
	s_add_u32 s36, s34, 0x84000
	s_addc_u32 s37, s35, 0
	global_store_dword v115, v183, s[36:37]
	v_mul_f32_e32 v184, v104, v168
	s_add_u32 s36, s34, 0xc0000
	s_addc_u32 s37, s35, 0
	global_store_dword v115, v184, s[36:37]
	v_mul_f32_e32 v185, v105, v169
	s_add_u32 s36, s34, 0xcc000
	s_addc_u32 s37, s35, 0
	global_store_dword v115, v185, s[36:37]
	v_mul_f32_e32 v186, v106, v170
	s_add_u32 s36, s34, 0xd8000
	s_addc_u32 s37, s35, 0
	global_store_dword v115, v186, s[36:37]
	v_mul_f32_e32 v187, v107, v171
	s_add_u32 s36, s34, 0xe4000
	s_addc_u32 s37, s35, 0
	global_store_dword v115, v187, s[36:37]
	v_mul_f32_e32 v188, v108, v172
	s_add_u32 s36, s34, 0x120000
	s_addc_u32 s37, s35, 0
	global_store_dword v115, v188, s[36:37]
	v_mul_f32_e32 v189, v109, v173
	s_add_u32 s36, s34, 0x12c000
	s_addc_u32 s37, s35, 0
	global_store_dword v115, v189, s[36:37]
	v_mul_f32_e32 v190, v110, v174
	s_add_u32 s36, s34, 0x138000
	s_addc_u32 s37, s35, 0
	global_store_dword v115, v190, s[36:37]
	v_mul_f32_e32 v191, v111, v175
	s_add_u32 s36, s34, 0x144000
	s_addc_u32 s37, s35, 0
	global_store_dword v115, v191, s[36:37]
	s_add_i32 s28, s21, 32
	s_sub_i32 s29, s28, 0x300
	s_cmp_ge_u32 s28, 0x300
	s_cselect_b32 s29, s29, s28
	s_mul_i32 s30, s28, 0xc000
	s_lshl_b32 s35, s20, 2
	s_add_u32 s30, s30, s35
	s_add_u32 s34, s14, s30
	s_addc_u32 s35, s15, 0
	s_add_i32 s30, s21, 64
	s_lshl_b32 s30, s30, 2
	s_add_u32 s26, s6, s30
	s_addc_u32 s27, s7, 0
	global_load_dword v64, v115, s[26:27]
	s_add_u32 s26, s26, 0x1800
	s_addc_u32 s27, s27, 0
	global_load_dword v65, v115, s[26:27]
	s_add_u32 s26, s26, 0x1800
	s_addc_u32 s27, s27, 0
	global_load_dword v66, v115, s[26:27]
	s_add_u32 s26, s26, 0x1800
	s_addc_u32 s27, s27, 0
	global_load_dword v67, v115, s[26:27]
	s_add_u32 s26, s26, 0x1800
	s_addc_u32 s27, s27, 0
	global_load_dword v68, v115, s[26:27]
	s_add_u32 s26, s26, 0x1800
	s_addc_u32 s27, s27, 0
	global_load_dword v69, v115, s[26:27]
	s_add_u32 s26, s26, 0x1800
	s_addc_u32 s27, s27, 0
	global_load_dword v70, v115, s[26:27]
	s_add_u32 s26, s26, 0x1800
	s_addc_u32 s27, s27, 0
	global_load_dword v71, v115, s[26:27]
	s_add_u32 s26, s26, 0x1800
	s_addc_u32 s27, s27, 0
	global_load_dword v72, v115, s[26:27]
	s_add_u32 s26, s26, 0x1800
	s_addc_u32 s27, s27, 0
	global_load_dword v73, v115, s[26:27]
	s_add_u32 s26, s26, 0x1800
	s_addc_u32 s27, s27, 0
	global_load_dword v74, v115, s[26:27]
	s_add_u32 s26, s26, 0x1800
	s_addc_u32 s27, s27, 0
	global_load_dword v75, v115, s[26:27]
	s_add_u32 s26, s26, 0x1800
	s_addc_u32 s27, s27, 0
	global_load_dword v76, v115, s[26:27]
	s_add_u32 s26, s26, 0x1800
	s_addc_u32 s27, s27, 0
	global_load_dword v77, v115, s[26:27]
	s_add_u32 s26, s26, 0x1800
	s_addc_u32 s27, s27, 0
	global_load_dword v78, v115, s[26:27]
	s_add_u32 s26, s26, 0x1800
	s_addc_u32 s27, s27, 0
	global_load_dword v79, v115, s[26:27]
	s_add_u32 s26, s26, 0x1800
	s_addc_u32 s27, s27, 0
	global_load_dword v80, v115, s[26:27]
	s_add_u32 s26, s26, 0x1800
	s_addc_u32 s27, s27, 0
	global_load_dword v81, v115, s[26:27]
	s_add_u32 s26, s26, 0x1800
	s_addc_u32 s27, s27, 0
	global_load_dword v82, v115, s[26:27]
	s_add_u32 s26, s26, 0x1800
	s_addc_u32 s27, s27, 0
	global_load_dword v83, v115, s[26:27]
	s_add_u32 s26, s26, 0x1800
	s_addc_u32 s27, s27, 0
	global_load_dword v84, v115, s[26:27]
	s_add_u32 s26, s26, 0x1800
	s_addc_u32 s27, s27, 0
	global_load_dword v85, v115, s[26:27]
	s_add_u32 s26, s26, 0x1800
	s_addc_u32 s27, s27, 0
	global_load_dword v86, v115, s[26:27]
	s_add_u32 s26, s26, 0x1800
	s_addc_u32 s27, s27, 0
	global_load_dword v87, v115, s[26:27]
	s_add_u32 s26, s26, 0x1800
	s_addc_u32 s27, s27, 0
	global_load_dword v88, v115, s[26:27]
	s_add_u32 s26, s26, 0x1800
	s_addc_u32 s27, s27, 0
	global_load_dword v89, v115, s[26:27]
	s_add_u32 s26, s26, 0x1800
	s_addc_u32 s27, s27, 0
	global_load_dword v90, v115, s[26:27]
	s_add_u32 s26, s26, 0x1800
	s_addc_u32 s27, s27, 0
	global_load_dword v91, v115, s[26:27]
	s_add_u32 s26, s26, 0x1800
	s_addc_u32 s27, s27, 0
	global_load_dword v92, v115, s[26:27]
	s_add_u32 s26, s26, 0x1800
	s_addc_u32 s27, s27, 0
	global_load_dword v93, v115, s[26:27]
	s_add_u32 s26, s26, 0x1800
	s_addc_u32 s27, s27, 0
	global_load_dword v94, v115, s[26:27]
	s_add_u32 s26, s26, 0x1800
	s_addc_u32 s27, s27, 0
	global_load_dword v95, v115, s[26:27]
	s_waitcnt vmcnt(48)
; __device__ __forceinline__ void kraw_items(const Args& a, int gw, int NGW, int lane) {
;     ...
;             for (int ci = 0; ci < 12; ++ci) { const int c = c0 + 12 * cb + ci;
;                 float acc = 0.f;
; #pragma unroll
;                 for (int jj = 0; jj < 64; ++jj) acc += h[jj] * __builtin_bit_cast(float, __builtin_amdgcn_readlane(__builtin_bit_cast(int, wv[ci]), jj));
;                 const int cm = c % 768;
;                 const float delta = fabsf(-3.0701134573253945f + (float)cm * ((-15.350567286626973f + 3.0701134573253945f) / 767.0f));
;                 KR[(size_t)c * (LP + LS) + p] = acc * __expf(-tt * delta); }
	v_mfma_f32_32x32x2_f32 v[96:111], v128, v0, 0
	v_mfma_f32_32x32x2_f32 v[96:111], v129, v1, v[96:111]
	v_mfma_f32_32x32x2_f32 v[96:111], v130, v2, v[96:111]
	v_mfma_f32_32x32x2_f32 v[96:111], v131, v3, v[96:111]
	v_mfma_f32_32x32x2_f32 v[96:111], v132, v4, v[96:111]
	v_mfma_f32_32x32x2_f32 v[96:111], v133, v5, v[96:111]
	v_mfma_f32_32x32x2_f32 v[96:111], v134, v6, v[96:111]
	v_mfma_f32_32x32x2_f32 v[96:111], v135, v7, v[96:111]
	v_mfma_f32_32x32x2_f32 v[96:111], v136, v8, v[96:111]
	v_mfma_f32_32x32x2_f32 v[96:111], v137, v9, v[96:111]
	v_mfma_f32_32x32x2_f32 v[96:111], v138, v10, v[96:111]
	v_mfma_f32_32x32x2_f32 v[96:111], v139, v11, v[96:111]
	v_mfma_f32_32x32x2_f32 v[96:111], v140, v12, v[96:111]
	v_mfma_f32_32x32x2_f32 v[96:111], v141, v13, v[96:111]
	v_mfma_f32_32x32x2_f32 v[96:111], v142, v14, v[96:111]
	v_mfma_f32_32x32x2_f32 v[96:111], v143, v15, v[96:111]
	v_mfma_f32_32x32x2_f32 v[96:111], v144, v16, v[96:111]
	v_mfma_f32_32x32x2_f32 v[96:111], v145, v17, v[96:111]
	v_mfma_f32_32x32x2_f32 v[96:111], v146, v18, v[96:111]
	v_mfma_f32_32x32x2_f32 v[96:111], v147, v19, v[96:111]
	v_mfma_f32_32x32x2_f32 v[96:111], v148, v20, v[96:111]
	v_mfma_f32_32x32x2_f32 v[96:111], v149, v21, v[96:111]
	v_mfma_f32_32x32x2_f32 v[96:111], v150, v22, v[96:111]
	v_mfma_f32_32x32x2_f32 v[96:111], v151, v23, v[96:111]
	v_mfma_f32_32x32x2_f32 v[96:111], v152, v24, v[96:111]
	v_mfma_f32_32x32x2_f32 v[96:111], v153, v25, v[96:111]
	v_mfma_f32_32x32x2_f32 v[96:111], v154, v26, v[96:111]
	v_mfma_f32_32x32x2_f32 v[96:111], v155, v27, v[96:111]
	v_mfma_f32_32x32x2_f32 v[96:111], v156, v28, v[96:111]
	v_mfma_f32_32x32x2_f32 v[96:111], v157, v29, v[96:111]
	v_mfma_f32_32x32x2_f32 v[96:111], v158, v30, v[96:111]
	v_mfma_f32_32x32x2_f32 v[96:111], v159, v31, v[96:111]
	s_add_i32 s30, s29, 0
	v_add_u32_e32 v119, s30, v118
	v_cvt_f32_u32_e32 v119, v119
	v_fmamk_f32 v119, v119, 0xbc83298c, v120
	v_mul_f32_e64 v119, v117, |v119|
	v_mul_f32_e32 v119, 0x3fb8aa3b, v119
	v_exp_f32_e32 v160, v119
	s_add_i32 s30, s29, 1
	v_add_u32_e32 v119, s30, v118
	v_cvt_f32_u32_e32 v119, v119
	v_fmamk_f32 v119, v119, 0xbc83298c, v120
	v_mul_f32_e64 v119, v117, |v119|
	v_mul_f32_e32 v119, 0x3fb8aa3b, v119
	v_exp_f32_e32 v161, v119
	s_add_i32 s30, s29, 2
	v_add_u32_e32 v119, s30, v118
	v_cvt_f32_u32_e32 v119, v119
	v_fmamk_f32 v119, v119, 0xbc83298c, v120
	v_mul_f32_e64 v119, v117, |v119|
	v_mul_f32_e32 v119, 0x3fb8aa3b, v119
	v_exp_f32_e32 v162, v119
	s_add_i32 s30, s29, 3
	v_add_u32_e32 v119, s30, v118
	v_cvt_f32_u32_e32 v119, v119
	v_fmamk_f32 v119, v119, 0xbc83298c, v120
	v_mul_f32_e64 v119, v117, |v119|
	v_mul_f32_e32 v119, 0x3fb8aa3b, v119
	v_exp_f32_e32 v163, v119
	s_add_i32 s30, s29, 8
	v_add_u32_e32 v119, s30, v118
	v_cvt_f32_u32_e32 v119, v119
	v_fmamk_f32 v119, v119, 0xbc83298c, v120
	v_mul_f32_e64 v119, v117, |v119|
	v_mul_f32_e32 v119, 0x3fb8aa3b, v119
	v_exp_f32_e32 v164, v119
	s_add_i32 s30, s29, 9
	v_add_u32_e32 v119, s30, v118
	v_cvt_f32_u32_e32 v119, v119
	v_fmamk_f32 v119, v119, 0xbc83298c, v120
	v_mul_f32_e64 v119, v117, |v119|
	v_mul_f32_e32 v119, 0x3fb8aa3b, v119
	v_exp_f32_e32 v165, v119
	s_add_i32 s30, s29, 10
	v_add_u32_e32 v119, s30, v118
	v_cvt_f32_u32_e32 v119, v119
	v_fmamk_f32 v119, v119, 0xbc83298c, v120
	v_mul_f32_e64 v119, v117, |v119|
	v_mul_f32_e32 v119, 0x3fb8aa3b, v119
	v_exp_f32_e32 v166, v119
	s_add_i32 s30, s29, 11
	v_add_u32_e32 v119, s30, v118
	v_cvt_f32_u32_e32 v119, v119
	v_fmamk_f32 v119, v119, 0xbc83298c, v120
	v_mul_f32_e64 v119, v117, |v119|
	v_mul_f32_e32 v119, 0x3fb8aa3b, v119
	v_exp_f32_e32 v167, v119
	s_add_i32 s30, s29, 16
	v_add_u32_e32 v119, s30, v118
	v_cvt_f32_u32_e32 v119, v119
	v_fmamk_f32 v119, v119, 0xbc83298c, v120
	v_mul_f32_e64 v119, v117, |v119|
	v_mul_f32_e32 v119, 0x3fb8aa3b, v119
	v_exp_f32_e32 v168, v119
	s_add_i32 s30, s29, 17
	v_add_u32_e32 v119, s30, v118
	v_cvt_f32_u32_e32 v119, v119
	v_fmamk_f32 v119, v119, 0xbc83298c, v120
	v_mul_f32_e64 v119, v117, |v119|
	v_mul_f32_e32 v119, 0x3fb8aa3b, v119
	v_exp_f32_e32 v169, v119
	s_add_i32 s30, s29, 18
	v_add_u32_e32 v119, s30, v118
	v_cvt_f32_u32_e32 v119, v119
	v_fmamk_f32 v119, v119, 0xbc83298c, v120
	v_mul_f32_e64 v119, v117, |v119|
	v_mul_f32_e32 v119, 0x3fb8aa3b, v119
	v_exp_f32_e32 v170, v119
	s_add_i32 s30, s29, 19
	v_add_u32_e32 v119, s30, v118
	v_cvt_f32_u32_e32 v119, v119
	v_fmamk_f32 v119, v119, 0xbc83298c, v120
	v_mul_f32_e64 v119, v117, |v119|
	v_mul_f32_e32 v119, 0x3fb8aa3b, v119
	v_exp_f32_e32 v171, v119
	s_add_i32 s30, s29, 24
	v_add_u32_e32 v119, s30, v118
	v_cvt_f32_u32_e32 v119, v119
	v_fmamk_f32 v119, v119, 0xbc83298c, v120
	v_mul_f32_e64 v119, v117, |v119|
	v_mul_f32_e32 v119, 0x3fb8aa3b, v119
	v_exp_f32_e32 v172, v119
	s_add_i32 s30, s29, 25
	v_add_u32_e32 v119, s30, v118
	v_cvt_f32_u32_e32 v119, v119
	v_fmamk_f32 v119, v119, 0xbc83298c, v120
	v_mul_f32_e64 v119, v117, |v119|
	v_mul_f32_e32 v119, 0x3fb8aa3b, v119
	v_exp_f32_e32 v173, v119
	s_add_i32 s30, s29, 26
	v_add_u32_e32 v119, s30, v118
	v_cvt_f32_u32_e32 v119, v119
	v_fmamk_f32 v119, v119, 0xbc83298c, v120
	v_mul_f32_e64 v119, v117, |v119|
	v_mul_f32_e32 v119, 0x3fb8aa3b, v119
	v_exp_f32_e32 v174, v119
	s_add_i32 s30, s29, 27
	v_add_u32_e32 v119, s30, v118
	v_cvt_f32_u32_e32 v119, v119
	v_fmamk_f32 v119, v119, 0xbc83298c, v120
	v_mul_f32_e64 v119, v117, |v119|
	v_mul_f32_e32 v119, 0x3fb8aa3b, v119
	v_exp_f32_e32 v175, v119
	s_nop 7
	v_mul_f32_e32 v176, v96, v160
	s_mov_b64 s[36:37], s[34:35]
	global_store_dword v115, v176, s[36:37]
	v_mul_f32_e32 v177, v97, v161
	s_add_u32 s36, s34, 0xc000
	s_addc_u32 s37, s35, 0
	global_store_dword v115, v177, s[36:37]
	v_mul_f32_e32 v178, v98, v162
; __device__ __forceinline__ void kraw_items(const Args& a, int gw, int NGW, int lane) {
;     ...
;     for (int it = gw; it < 192 * 32; it += NGW) {
;         const int pg = it >> 5, cgp = it & 31, p = pg * 64 + lane, c0 = cgp * 48;
;         float h[64];
; #pragma unroll
;         for (int q = 0; q < 16; ++q) { const f32x4 t = *(const f32x4*)(H3 + (size_t)p * 64 + 4 * q); h[4 * q] = t.x; h[4 * q + 1] = t.y; h[4 * q + 2] = t.z; h[4 * q + 3] = t.w; }
;         const int grp = p >= LP, tpos = p - grp * LP, L = grp ? LS : LP;
;         const float tt = (float)tpos * (1.0f / (float)(L - 1));
; #pragma unroll 1
;         for (int cb = 0; cb < 4; ++cb) {
;             const float* wr = a.in[I_FWOUT] + lane * 1536 + c0 + 12 * cb;
;             const f32x4 w0 = *(const f32x4*)(wr), w1 = *(const f32x4*)(wr + 4), w2 = *(const f32x4*)(wr + 8);
;             float wv[12] = {w0.x, w0.y, w0.z, w0.w, w1.x, w1.y, w1.z, w1.w, w2.x, w2.y, w2.z, w2.w};
	s_add_u32 s36, s34, 0x18000
	s_addc_u32 s37, s35, 0
	global_store_dword v115, v178, s[36:37]
	v_mul_f32_e32 v179, v99, v163
	s_add_u32 s36, s34, 0x24000
	s_addc_u32 s37, s35, 0
	global_store_dword v115, v179, s[36:37]
	v_mul_f32_e32 v180, v100, v164
	s_add_u32 s36, s34, 0x60000
	s_addc_u32 s37, s35, 0
	global_store_dword v115, v180, s[36:37]
	v_mul_f32_e32 v181, v101, v165
	s_add_u32 s36, s34, 0x6c000
	s_addc_u32 s37, s35, 0
	global_store_dword v115, v181, s[36:37]
	v_mul_f32_e32 v182, v102, v166
	s_add_u32 s36, s34, 0x78000
	s_addc_u32 s37, s35, 0
	global_store_dword v115, v182, s[36:37]
	v_mul_f32_e32 v183, v103, v167
	s_add_u32 s36, s34, 0x84000
	s_addc_u32 s37, s35, 0
	global_store_dword v115, v183, s[36:37]
	v_mul_f32_e32 v184, v104, v168
	s_add_u32 s36, s34, 0xc0000
	s_addc_u32 s37, s35, 0
	global_store_dword v115, v184, s[36:37]
	v_mul_f32_e32 v185, v105, v169
	s_add_u32 s36, s34, 0xcc000
	s_addc_u32 s37, s35, 0
	global_store_dword v115, v185, s[36:37]
	v_mul_f32_e32 v186, v106, v170
	s_add_u32 s36, s34, 0xd8000
	s_addc_u32 s37, s35, 0
	global_store_dword v115, v186, s[36:37]
	v_mul_f32_e32 v187, v107, v171
	s_add_u32 s36, s34, 0xe4000
	s_addc_u32 s37, s35, 0
	global_store_dword v115, v187, s[36:37]
	v_mul_f32_e32 v188, v108, v172
	s_add_u32 s36, s34, 0x120000
	s_addc_u32 s37, s35, 0
	global_store_dword v115, v188, s[36:37]
	v_mul_f32_e32 v189, v109, v173
	s_add_u32 s36, s34, 0x12c000
	s_addc_u32 s37, s35, 0
	global_store_dword v115, v189, s[36:37]
	v_mul_f32_e32 v190, v110, v174
	s_add_u32 s36, s34, 0x138000
	s_addc_u32 s37, s35, 0
	global_store_dword v115, v190, s[36:37]
	v_mul_f32_e32 v191, v111, v175
	s_add_u32 s36, s34, 0x144000
	s_addc_u32 s37, s35, 0
	global_store_dword v115, v191, s[36:37]
	s_add_i32 s28, s21, 64
	s_sub_i32 s29, s28, 0x300
	s_cmp_ge_u32 s28, 0x300
	s_cselect_b32 s29, s29, s28
	s_mul_i32 s30, s28, 0xc000
	s_lshl_b32 s35, s20, 2
	s_add_u32 s30, s30, s35
	s_add_u32 s34, s14, s30
	s_addc_u32 s35, s15, 0
	s_add_i32 s17, s16, 0x800
	s_lshr_b32 s18, s17, 4
	s_and_b32 s19, s17, 15
	s_lshl_b32 s20, s18, 5
	s_mul_i32 s21, s19, 0x60
	s_lshl_b32 s30, s20, 8
	s_add_u32 s24, s10, s30
	s_addc_u32 s25, s11, 0
	global_load_dwordx4 v[32:35], v114, s[24:25] offset:0
	global_load_dwordx4 v[36:39], v114, s[24:25] offset:16
	global_load_dwordx4 v[40:43], v114, s[24:25] offset:32
	global_load_dwordx4 v[44:47], v114, s[24:25] offset:48
	global_load_dwordx4 v[48:51], v114, s[24:25] offset:64
	global_load_dwordx4 v[52:55], v114, s[24:25] offset:80
	global_load_dwordx4 v[56:59], v114, s[24:25] offset:96
	global_load_dwordx4 v[60:63], v114, s[24:25] offset:112
	s_add_i32 s30, s21, 0
	s_lshl_b32 s30, s30, 2
	s_add_u32 s26, s6, s30
	s_addc_u32 s27, s7, 0
	global_load_dword v128, v115, s[26:27]
	s_add_u32 s26, s26, 0x1800
	s_addc_u32 s27, s27, 0
	global_load_dword v129, v115, s[26:27]
	s_add_u32 s26, s26, 0x1800
	s_addc_u32 s27, s27, 0
	global_load_dword v130, v115, s[26:27]
	s_add_u32 s26, s26, 0x1800
	s_addc_u32 s27, s27, 0
	global_load_dword v131, v115, s[26:27]
	s_add_u32 s26, s26, 0x1800
	s_addc_u32 s27, s27, 0
	global_load_dword v132, v115, s[26:27]
	s_add_u32 s26, s26, 0x1800
	s_addc_u32 s27, s27, 0
	global_load_dword v133, v115, s[26:27]
	s_add_u32 s26, s26, 0x1800
	s_addc_u32 s27, s27, 0
	global_load_dword v134, v115, s[26:27]
	s_add_u32 s26, s26, 0x1800
	s_addc_u32 s27, s27, 0
	global_load_dword v135, v115, s[26:27]
	s_add_u32 s26, s26, 0x1800
	s_addc_u32 s27, s27, 0
	global_load_dword v136, v115, s[26:27]
	s_add_u32 s26, s26, 0x1800
	s_addc_u32 s27, s27, 0
	global_load_dword v137, v115, s[26:27]
	s_add_u32 s26, s26, 0x1800
	s_addc_u32 s27, s27, 0
	global_load_dword v138, v115, s[26:27]
	s_add_u32 s26, s26, 0x1800
	s_addc_u32 s27, s27, 0
	global_load_dword v139, v115, s[26:27]
	s_add_u32 s26, s26, 0x1800
	s_addc_u32 s27, s27, 0
	global_load_dword v140, v115, s[26:27]
	s_add_u32 s26, s26, 0x1800
	s_addc_u32 s27, s27, 0
	global_load_dword v141, v115, s[26:27]
	s_add_u32 s26, s26, 0x1800
	s_addc_u32 s27, s27, 0
	global_load_dword v142, v115, s[26:27]
	s_add_u32 s26, s26, 0x1800
	s_addc_u32 s27, s27, 0
	global_load_dword v143, v115, s[26:27]
	s_add_u32 s26, s26, 0x1800
	s_addc_u32 s27, s27, 0
	global_load_dword v144, v115, s[26:27]
	s_add_u32 s26, s26, 0x1800
	s_addc_u32 s27, s27, 0
	global_load_dword v145, v115, s[26:27]
	s_add_u32 s26, s26, 0x1800
	s_addc_u32 s27, s27, 0
	global_load_dword v146, v115, s[26:27]
	s_add_u32 s26, s26, 0x1800
	s_addc_u32 s27, s27, 0
	global_load_dword v147, v115, s[26:27]
	s_add_u32 s26, s26, 0x1800
	s_addc_u32 s27, s27, 0
	global_load_dword v148, v115, s[26:27]
	s_add_u32 s26, s26, 0x1800
	s_addc_u32 s27, s27, 0
	global_load_dword v149, v115, s[26:27]
	s_add_u32 s26, s26, 0x1800
	s_addc_u32 s27, s27, 0
	global_load_dword v150, v115, s[26:27]
	s_add_u32 s26, s26, 0x1800
	s_addc_u32 s27, s27, 0
	global_load_dword v151, v115, s[26:27]
	s_add_u32 s26, s26, 0x1800
	s_addc_u32 s27, s27, 0
	global_load_dword v152, v115, s[26:27]
	s_add_u32 s26, s26, 0x1800
	s_addc_u32 s27, s27, 0
	global_load_dword v153, v115, s[26:27]
	s_add_u32 s26, s26, 0x1800
	s_addc_u32 s27, s27, 0
	global_load_dword v154, v115, s[26:27]
	s_add_u32 s26, s26, 0x1800
	s_addc_u32 s27, s27, 0
	global_load_dword v155, v115, s[26:27]
	s_add_u32 s26, s26, 0x1800
	s_addc_u32 s27, s27, 0
	global_load_dword v156, v115, s[26:27]
	s_add_u32 s26, s26, 0x1800
	s_addc_u32 s27, s27, 0
	global_load_dword v157, v115, s[26:27]
	s_add_u32 s26, s26, 0x1800
	s_addc_u32 s27, s27, 0
	global_load_dword v158, v115, s[26:27]
	s_add_u32 s26, s26, 0x1800
	s_addc_u32 s27, s27, 0
	global_load_dword v159, v115, s[26:27]
	s_waitcnt vmcnt(56)
; __device__ __forceinline__ void kraw_items(const Args& a, int gw, int NGW, int lane) {
;     ...
;             for (int ci = 0; ci < 12; ++ci) { const int c = c0 + 12 * cb + ci;
;                 float acc = 0.f;
; #pragma unroll
;                 for (int jj = 0; jj < 64; ++jj) acc += h[jj] * __builtin_bit_cast(float, __builtin_amdgcn_readlane(__builtin_bit_cast(int, wv[ci]), jj));
;                 const int cm = c % 768;
;                 const float delta = fabsf(-3.0701134573253945f + (float)cm * ((-15.350567286626973f + 3.0701134573253945f) / 767.0f));
;                 KR[(size_t)c * (LP + LS) + p] = acc * __expf(-tt * delta); }
	v_mfma_f32_32x32x2_f32 v[96:111], v64, v0, 0
	v_mfma_f32_32x32x2_f32 v[96:111], v65, v1, v[96:111]
	v_mfma_f32_32x32x2_f32 v[96:111], v66, v2, v[96:111]
	v_mfma_f32_32x32x2_f32 v[96:111], v67, v3, v[96:111]
	v_mfma_f32_32x32x2_f32 v[96:111], v68, v4, v[96:111]
	v_mfma_f32_32x32x2_f32 v[96:111], v69, v5, v[96:111]
	v_mfma_f32_32x32x2_f32 v[96:111], v70, v6, v[96:111]
	v_mfma_f32_32x32x2_f32 v[96:111], v71, v7, v[96:111]
	v_mfma_f32_32x32x2_f32 v[96:111], v72, v8, v[96:111]
	v_mfma_f32_32x32x2_f32 v[96:111], v73, v9, v[96:111]
	v_mfma_f32_32x32x2_f32 v[96:111], v74, v10, v[96:111]
	v_mfma_f32_32x32x2_f32 v[96:111], v75, v11, v[96:111]
	v_mfma_f32_32x32x2_f32 v[96:111], v76, v12, v[96:111]
	v_mfma_f32_32x32x2_f32 v[96:111], v77, v13, v[96:111]
	v_mfma_f32_32x32x2_f32 v[96:111], v78, v14, v[96:111]
	v_mfma_f32_32x32x2_f32 v[96:111], v79, v15, v[96:111]
	v_mfma_f32_32x32x2_f32 v[96:111], v80, v16, v[96:111]
	v_mfma_f32_32x32x2_f32 v[96:111], v81, v17, v[96:111]
	v_mfma_f32_32x32x2_f32 v[96:111], v82, v18, v[96:111]
	v_mfma_f32_32x32x2_f32 v[96:111], v83, v19, v[96:111]
	v_mfma_f32_32x32x2_f32 v[96:111], v84, v20, v[96:111]
	v_mfma_f32_32x32x2_f32 v[96:111], v85, v21, v[96:111]
	v_mfma_f32_32x32x2_f32 v[96:111], v86, v22, v[96:111]
	v_mfma_f32_32x32x2_f32 v[96:111], v87, v23, v[96:111]
	v_mfma_f32_32x32x2_f32 v[96:111], v88, v24, v[96:111]
	v_mfma_f32_32x32x2_f32 v[96:111], v89, v25, v[96:111]
	v_mfma_f32_32x32x2_f32 v[96:111], v90, v26, v[96:111]
	v_mfma_f32_32x32x2_f32 v[96:111], v91, v27, v[96:111]
	v_mfma_f32_32x32x2_f32 v[96:111], v92, v28, v[96:111]
	v_mfma_f32_32x32x2_f32 v[96:111], v93, v29, v[96:111]
	v_mfma_f32_32x32x2_f32 v[96:111], v94, v30, v[96:111]
	v_mfma_f32_32x32x2_f32 v[96:111], v95, v31, v[96:111]
	s_add_i32 s30, s29, 0
	v_add_u32_e32 v119, s30, v118
	v_cvt_f32_u32_e32 v119, v119
	v_fmamk_f32 v119, v119, 0xbc83298c, v120
	v_mul_f32_e64 v119, v117, |v119|
	v_mul_f32_e32 v119, 0x3fb8aa3b, v119
	v_exp_f32_e32 v160, v119
	s_add_i32 s30, s29, 1
	v_add_u32_e32 v119, s30, v118
	v_cvt_f32_u32_e32 v119, v119
	v_fmamk_f32 v119, v119, 0xbc83298c, v120
	v_mul_f32_e64 v119, v117, |v119|
	v_mul_f32_e32 v119, 0x3fb8aa3b, v119
	v_exp_f32_e32 v161, v119
	s_add_i32 s30, s29, 2
	v_add_u32_e32 v119, s30, v118
	v_cvt_f32_u32_e32 v119, v119
	v_fmamk_f32 v119, v119, 0xbc83298c, v120
	v_mul_f32_e64 v119, v117, |v119|
	v_mul_f32_e32 v119, 0x3fb8aa3b, v119
	v_exp_f32_e32 v162, v119
	s_add_i32 s30, s29, 3
	v_add_u32_e32 v119, s30, v118
	v_cvt_f32_u32_e32 v119, v119
	v_fmamk_f32 v119, v119, 0xbc83298c, v120
	v_mul_f32_e64 v119, v117, |v119|
	v_mul_f32_e32 v119, 0x3fb8aa3b, v119
	v_exp_f32_e32 v163, v119
	s_add_i32 s30, s29, 8
	v_add_u32_e32 v119, s30, v118
	v_cvt_f32_u32_e32 v119, v119
	v_fmamk_f32 v119, v119, 0xbc83298c, v120
	v_mul_f32_e64 v119, v117, |v119|
	v_mul_f32_e32 v119, 0x3fb8aa3b, v119
	v_exp_f32_e32 v164, v119
	s_add_i32 s30, s29, 9
	v_add_u32_e32 v119, s30, v118
	v_cvt_f32_u32_e32 v119, v119
	v_fmamk_f32 v119, v119, 0xbc83298c, v120
	v_mul_f32_e64 v119, v117, |v119|
	v_mul_f32_e32 v119, 0x3fb8aa3b, v119
	v_exp_f32_e32 v165, v119
	s_add_i32 s30, s29, 10
	v_add_u32_e32 v119, s30, v118
	v_cvt_f32_u32_e32 v119, v119
	v_fmamk_f32 v119, v119, 0xbc83298c, v120
	v_mul_f32_e64 v119, v117, |v119|
	v_mul_f32_e32 v119, 0x3fb8aa3b, v119
	v_exp_f32_e32 v166, v119
	s_add_i32 s30, s29, 11
	v_add_u32_e32 v119, s30, v118
	v_cvt_f32_u32_e32 v119, v119
	v_fmamk_f32 v119, v119, 0xbc83298c, v120
	v_mul_f32_e64 v119, v117, |v119|
	v_mul_f32_e32 v119, 0x3fb8aa3b, v119
	v_exp_f32_e32 v167, v119
	s_add_i32 s30, s29, 16
	v_add_u32_e32 v119, s30, v118
	v_cvt_f32_u32_e32 v119, v119
	v_fmamk_f32 v119, v119, 0xbc83298c, v120
	v_mul_f32_e64 v119, v117, |v119|
	v_mul_f32_e32 v119, 0x3fb8aa3b, v119
	v_exp_f32_e32 v168, v119
	s_add_i32 s30, s29, 17
	v_add_u32_e32 v119, s30, v118
	v_cvt_f32_u32_e32 v119, v119
	v_fmamk_f32 v119, v119, 0xbc83298c, v120
	v_mul_f32_e64 v119, v117, |v119|
	v_mul_f32_e32 v119, 0x3fb8aa3b, v119
	v_exp_f32_e32 v169, v119
	s_add_i32 s30, s29, 18
	v_add_u32_e32 v119, s30, v118
	v_cvt_f32_u32_e32 v119, v119
	v_fmamk_f32 v119, v119, 0xbc83298c, v120
	v_mul_f32_e64 v119, v117, |v119|
	v_mul_f32_e32 v119, 0x3fb8aa3b, v119
	v_exp_f32_e32 v170, v119
	s_add_i32 s30, s29, 19
	v_add_u32_e32 v119, s30, v118
	v_cvt_f32_u32_e32 v119, v119
	v_fmamk_f32 v119, v119, 0xbc83298c, v120
	v_mul_f32_e64 v119, v117, |v119|
	v_mul_f32_e32 v119, 0x3fb8aa3b, v119
	v_exp_f32_e32 v171, v119
	s_add_i32 s30, s29, 24
	v_add_u32_e32 v119, s30, v118
	v_cvt_f32_u32_e32 v119, v119
	v_fmamk_f32 v119, v119, 0xbc83298c, v120
	v_mul_f32_e64 v119, v117, |v119|
	v_mul_f32_e32 v119, 0x3fb8aa3b, v119
	v_exp_f32_e32 v172, v119
	s_add_i32 s30, s29, 25
	v_add_u32_e32 v119, s30, v118
	v_cvt_f32_u32_e32 v119, v119
	v_fmamk_f32 v119, v119, 0xbc83298c, v120
	v_mul_f32_e64 v119, v117, |v119|
	v_mul_f32_e32 v119, 0x3fb8aa3b, v119
	v_exp_f32_e32 v173, v119
	s_add_i32 s30, s29, 26
	v_add_u32_e32 v119, s30, v118
	v_cvt_f32_u32_e32 v119, v119
	v_fmamk_f32 v119, v119, 0xbc83298c, v120
	v_mul_f32_e64 v119, v117, |v119|
	v_mul_f32_e32 v119, 0x3fb8aa3b, v119
	v_exp_f32_e32 v174, v119
	s_add_i32 s30, s29, 27
	v_add_u32_e32 v119, s30, v118
	v_cvt_f32_u32_e32 v119, v119
	v_fmamk_f32 v119, v119, 0xbc83298c, v120
	v_mul_f32_e64 v119, v117, |v119|
	v_mul_f32_e32 v119, 0x3fb8aa3b, v119
	v_exp_f32_e32 v175, v119
	s_nop 7
	v_mul_f32_e32 v176, v96, v160
	s_mov_b64 s[36:37], s[34:35]
	global_store_dword v115, v176, s[36:37]
	v_mul_f32_e32 v177, v97, v161
	s_add_u32 s36, s34, 0xc000
	s_addc_u32 s37, s35, 0
	global_store_dword v115, v177, s[36:37]
	v_mul_f32_e32 v178, v98, v162
	s_add_u32 s36, s34, 0x18000
; __device__ __forceinline__ void kraw_items(const Args& a, int gw, int NGW, int lane) {
;     ...
;         const int grp = p >= LP, tpos = p - grp * LP, L = grp ? LS : LP;
;         const float tt = (float)tpos * (1.0f / (float)(L - 1));
; #pragma unroll 1
;         for (int cb = 0; cb < 4; ++cb) {
;             const float* wr = a.in[I_FWOUT] + lane * 1536 + c0 + 12 * cb;
;             const f32x4 w0 = *(const f32x4*)(wr), w1 = *(const f32x4*)(wr + 4), w2 = *(const f32x4*)(wr + 8);
;             float wv[12] = {w0.x, w0.y, w0.z, w0.w, w1.x, w1.y, w1.z, w1.w, w2.x, w2.y, w2.z, w2.w};
; #pragma unroll
;             for (int ci = 0; ci < 12; ++ci) { const int c = c0 + 12 * cb + ci;
;                 float acc = 0.f;
; #pragma unroll
;                 for (int jj = 0; jj < 64; ++jj) acc += h[jj] * __builtin_bit_cast(float, __builtin_amdgcn_readlane(__builtin_bit_cast(int, wv[ci]), jj));
;                 const int cm = c % 768;
;                 const float delta = fabsf(-3.0701134573253945f + (float)cm * ((-15.350567286626973f + 3.0701134573253945f) / 767.0f));
;                 KR[(size_t)c * (LP + LS) + p] = acc * __expf(-tt * delta); }
	s_addc_u32 s37, s35, 0
	global_store_dword v115, v178, s[36:37]
	v_mul_f32_e32 v179, v99, v163
	s_add_u32 s36, s34, 0x24000
	s_addc_u32 s37, s35, 0
	global_store_dword v115, v179, s[36:37]
	v_mul_f32_e32 v180, v100, v164
	s_add_u32 s36, s34, 0x60000
	s_addc_u32 s37, s35, 0
	global_store_dword v115, v180, s[36:37]
	v_mul_f32_e32 v181, v101, v165
	s_add_u32 s36, s34, 0x6c000
	s_addc_u32 s37, s35, 0
	global_store_dword v115, v181, s[36:37]
	v_mul_f32_e32 v182, v102, v166
	s_add_u32 s36, s34, 0x78000
	s_addc_u32 s37, s35, 0
	global_store_dword v115, v182, s[36:37]
	v_mul_f32_e32 v183, v103, v167
	s_add_u32 s36, s34, 0x84000
	s_addc_u32 s37, s35, 0
	global_store_dword v115, v183, s[36:37]
	v_mul_f32_e32 v184, v104, v168
	s_add_u32 s36, s34, 0xc0000
	s_addc_u32 s37, s35, 0
	global_store_dword v115, v184, s[36:37]
	v_mul_f32_e32 v185, v105, v169
	s_add_u32 s36, s34, 0xcc000
	s_addc_u32 s37, s35, 0
	global_store_dword v115, v185, s[36:37]
	v_mul_f32_e32 v186, v106, v170
	s_add_u32 s36, s34, 0xd8000
	s_addc_u32 s37, s35, 0
	global_store_dword v115, v186, s[36:37]
	v_mul_f32_e32 v187, v107, v171
	s_add_u32 s36, s34, 0xe4000
	s_addc_u32 s37, s35, 0
	global_store_dword v115, v187, s[36:37]
	v_mul_f32_e32 v188, v108, v172
	s_add_u32 s36, s34, 0x120000
	s_addc_u32 s37, s35, 0
	global_store_dword v115, v188, s[36:37]
	v_mul_f32_e32 v189, v109, v173
	s_add_u32 s36, s34, 0x12c000
	s_addc_u32 s37, s35, 0
	global_store_dword v115, v189, s[36:37]
	v_mul_f32_e32 v190, v110, v174
	s_add_u32 s36, s34, 0x138000
	s_addc_u32 s37, s35, 0
	global_store_dword v115, v190, s[36:37]
	v_mul_f32_e32 v191, v111, v175
	s_add_u32 s36, s34, 0x144000
	s_addc_u32 s37, s35, 0
	global_store_dword v115, v191, s[36:37]
	s_add_i32 s28, s21, 0
	s_sub_i32 s29, s28, 0x300
	s_cmp_ge_u32 s28, 0x300
	s_cselect_b32 s29, s29, s28
	s_mul_i32 s30, s28, 0xc000
	s_lshl_b32 s35, s20, 2
	s_add_u32 s30, s30, s35
	s_add_u32 s34, s14, s30
	s_addc_u32 s35, s15, 0
	s_mov_b32 s22, 0xb9000400
	s_cmp_ge_u32 s20, 0x2000
	s_cselect_b32 s22, 0xb9800801, s22
	s_and_b32 s30, s20, 0x1fff
	v_add_u32_e32 v119, s30, v112
	v_cvt_f32_u32_e32 v119, v119
	v_mul_f32_e32 v117, s22, v119
	s_add_i32 s30, s21, 32
	s_lshl_b32 s30, s30, 2
	s_add_u32 s26, s6, s30
	s_addc_u32 s27, s7, 0
	global_load_dword v64, v115, s[26:27]
	s_add_u32 s26, s26, 0x1800
	s_addc_u32 s27, s27, 0
	global_load_dword v65, v115, s[26:27]
	s_add_u32 s26, s26, 0x1800
	s_addc_u32 s27, s27, 0
	global_load_dword v66, v115, s[26:27]
	s_add_u32 s26, s26, 0x1800
	s_addc_u32 s27, s27, 0
	global_load_dword v67, v115, s[26:27]
	s_add_u32 s26, s26, 0x1800
	s_addc_u32 s27, s27, 0
	global_load_dword v68, v115, s[26:27]
	s_add_u32 s26, s26, 0x1800
	s_addc_u32 s27, s27, 0
	global_load_dword v69, v115, s[26:27]
	s_add_u32 s26, s26, 0x1800
	s_addc_u32 s27, s27, 0
	global_load_dword v70, v115, s[26:27]
	s_add_u32 s26, s26, 0x1800
	s_addc_u32 s27, s27, 0
	global_load_dword v71, v115, s[26:27]
	s_add_u32 s26, s26, 0x1800
	s_addc_u32 s27, s27, 0
	global_load_dword v72, v115, s[26:27]
	s_add_u32 s26, s26, 0x1800
	s_addc_u32 s27, s27, 0
	global_load_dword v73, v115, s[26:27]
	s_add_u32 s26, s26, 0x1800
	s_addc_u32 s27, s27, 0
	global_load_dword v74, v115, s[26:27]
	s_add_u32 s26, s26, 0x1800
	s_addc_u32 s27, s27, 0
	global_load_dword v75, v115, s[26:27]
	s_add_u32 s26, s26, 0x1800
	s_addc_u32 s27, s27, 0
	global_load_dword v76, v115, s[26:27]
	s_add_u32 s26, s26, 0x1800
	s_addc_u32 s27, s27, 0
	global_load_dword v77, v115, s[26:27]
	s_add_u32 s26, s26, 0x1800
	s_addc_u32 s27, s27, 0
	global_load_dword v78, v115, s[26:27]
	s_add_u32 s26, s26, 0x1800
	s_addc_u32 s27, s27, 0
	global_load_dword v79, v115, s[26:27]
	s_add_u32 s26, s26, 0x1800
	s_addc_u32 s27, s27, 0
	global_load_dword v80, v115, s[26:27]
	s_add_u32 s26, s26, 0x1800
	s_addc_u32 s27, s27, 0
	global_load_dword v81, v115, s[26:27]
	s_add_u32 s26, s26, 0x1800
	s_addc_u32 s27, s27, 0
	global_load_dword v82, v115, s[26:27]
	s_add_u32 s26, s26, 0x1800
	s_addc_u32 s27, s27, 0
	global_load_dword v83, v115, s[26:27]
	s_add_u32 s26, s26, 0x1800
	s_addc_u32 s27, s27, 0
	global_load_dword v84, v115, s[26:27]
	s_add_u32 s26, s26, 0x1800
	s_addc_u32 s27, s27, 0
	global_load_dword v85, v115, s[26:27]
	s_add_u32 s26, s26, 0x1800
	s_addc_u32 s27, s27, 0
	global_load_dword v86, v115, s[26:27]
	s_add_u32 s26, s26, 0x1800
	s_addc_u32 s27, s27, 0
	global_load_dword v87, v115, s[26:27]
	s_add_u32 s26, s26, 0x1800
	s_addc_u32 s27, s27, 0
	global_load_dword v88, v115, s[26:27]
	s_add_u32 s26, s26, 0x1800
	s_addc_u32 s27, s27, 0
	global_load_dword v89, v115, s[26:27]
	s_add_u32 s26, s26, 0x1800
	s_addc_u32 s27, s27, 0
	global_load_dword v90, v115, s[26:27]
	s_add_u32 s26, s26, 0x1800
	s_addc_u32 s27, s27, 0
	global_load_dword v91, v115, s[26:27]
	s_add_u32 s26, s26, 0x1800
	s_addc_u32 s27, s27, 0
	global_load_dword v92, v115, s[26:27]
	s_add_u32 s26, s26, 0x1800
	s_addc_u32 s27, s27, 0
	global_load_dword v93, v115, s[26:27]
	s_add_u32 s26, s26, 0x1800
	s_addc_u32 s27, s27, 0
	global_load_dword v94, v115, s[26:27]
	s_add_u32 s26, s26, 0x1800
	s_addc_u32 s27, s27, 0
	global_load_dword v95, v115, s[26:27]
	s_waitcnt vmcnt(48)
; __device__ __forceinline__ void kraw_items(const Args& a, int gw, int NGW, int lane) {
;     ...
;             for (int ci = 0; ci < 12; ++ci) { const int c = c0 + 12 * cb + ci;
;                 float acc = 0.f;
; #pragma unroll
;                 for (int jj = 0; jj < 64; ++jj) acc += h[jj] * __builtin_bit_cast(float, __builtin_amdgcn_readlane(__builtin_bit_cast(int, wv[ci]), jj));
;                 const int cm = c % 768;
;                 const float delta = fabsf(-3.0701134573253945f + (float)cm * ((-15.350567286626973f + 3.0701134573253945f) / 767.0f));
;                 KR[(size_t)c * (LP + LS) + p] = acc * __expf(-tt * delta); }
	v_mfma_f32_32x32x2_f32 v[96:111], v128, v32, 0
	v_mfma_f32_32x32x2_f32 v[96:111], v129, v33, v[96:111]
	v_mfma_f32_32x32x2_f32 v[96:111], v130, v34, v[96:111]
	v_mfma_f32_32x32x2_f32 v[96:111], v131, v35, v[96:111]
	v_mfma_f32_32x32x2_f32 v[96:111], v132, v36, v[96:111]
	v_mfma_f32_32x32x2_f32 v[96:111], v133, v37, v[96:111]
	v_mfma_f32_32x32x2_f32 v[96:111], v134, v38, v[96:111]
	v_mfma_f32_32x32x2_f32 v[96:111], v135, v39, v[96:111]
	v_mfma_f32_32x32x2_f32 v[96:111], v136, v40, v[96:111]
	v_mfma_f32_32x32x2_f32 v[96:111], v137, v41, v[96:111]
	v_mfma_f32_32x32x2_f32 v[96:111], v138, v42, v[96:111]
	v_mfma_f32_32x32x2_f32 v[96:111], v139, v43, v[96:111]
	v_mfma_f32_32x32x2_f32 v[96:111], v140, v44, v[96:111]
	v_mfma_f32_32x32x2_f32 v[96:111], v141, v45, v[96:111]
	v_mfma_f32_32x32x2_f32 v[96:111], v142, v46, v[96:111]
	v_mfma_f32_32x32x2_f32 v[96:111], v143, v47, v[96:111]
	v_mfma_f32_32x32x2_f32 v[96:111], v144, v48, v[96:111]
	v_mfma_f32_32x32x2_f32 v[96:111], v145, v49, v[96:111]
	v_mfma_f32_32x32x2_f32 v[96:111], v146, v50, v[96:111]
	v_mfma_f32_32x32x2_f32 v[96:111], v147, v51, v[96:111]
	v_mfma_f32_32x32x2_f32 v[96:111], v148, v52, v[96:111]
	v_mfma_f32_32x32x2_f32 v[96:111], v149, v53, v[96:111]
	v_mfma_f32_32x32x2_f32 v[96:111], v150, v54, v[96:111]
	v_mfma_f32_32x32x2_f32 v[96:111], v151, v55, v[96:111]
	v_mfma_f32_32x32x2_f32 v[96:111], v152, v56, v[96:111]
	v_mfma_f32_32x32x2_f32 v[96:111], v153, v57, v[96:111]
	v_mfma_f32_32x32x2_f32 v[96:111], v154, v58, v[96:111]
	v_mfma_f32_32x32x2_f32 v[96:111], v155, v59, v[96:111]
	v_mfma_f32_32x32x2_f32 v[96:111], v156, v60, v[96:111]
	v_mfma_f32_32x32x2_f32 v[96:111], v157, v61, v[96:111]
	v_mfma_f32_32x32x2_f32 v[96:111], v158, v62, v[96:111]
	v_mfma_f32_32x32x2_f32 v[96:111], v159, v63, v[96:111]
	s_add_i32 s30, s29, 0
	v_add_u32_e32 v119, s30, v118
	v_cvt_f32_u32_e32 v119, v119
	v_fmamk_f32 v119, v119, 0xbc83298c, v120
	v_mul_f32_e64 v119, v117, |v119|
	v_mul_f32_e32 v119, 0x3fb8aa3b, v119
	v_exp_f32_e32 v160, v119
	s_add_i32 s30, s29, 1
	v_add_u32_e32 v119, s30, v118
	v_cvt_f32_u32_e32 v119, v119
	v_fmamk_f32 v119, v119, 0xbc83298c, v120
	v_mul_f32_e64 v119, v117, |v119|
	v_mul_f32_e32 v119, 0x3fb8aa3b, v119
	v_exp_f32_e32 v161, v119
	s_add_i32 s30, s29, 2
	v_add_u32_e32 v119, s30, v118
	v_cvt_f32_u32_e32 v119, v119
	v_fmamk_f32 v119, v119, 0xbc83298c, v120
	v_mul_f32_e64 v119, v117, |v119|
	v_mul_f32_e32 v119, 0x3fb8aa3b, v119
	v_exp_f32_e32 v162, v119
	s_add_i32 s30, s29, 3
	v_add_u32_e32 v119, s30, v118
	v_cvt_f32_u32_e32 v119, v119
	v_fmamk_f32 v119, v119, 0xbc83298c, v120
	v_mul_f32_e64 v119, v117, |v119|
	v_mul_f32_e32 v119, 0x3fb8aa3b, v119
	v_exp_f32_e32 v163, v119
	s_add_i32 s30, s29, 8
	v_add_u32_e32 v119, s30, v118
	v_cvt_f32_u32_e32 v119, v119
	v_fmamk_f32 v119, v119, 0xbc83298c, v120
	v_mul_f32_e64 v119, v117, |v119|
	v_mul_f32_e32 v119, 0x3fb8aa3b, v119
	v_exp_f32_e32 v164, v119
	s_add_i32 s30, s29, 9
	v_add_u32_e32 v119, s30, v118
	v_cvt_f32_u32_e32 v119, v119
	v_fmamk_f32 v119, v119, 0xbc83298c, v120
	v_mul_f32_e64 v119, v117, |v119|
	v_mul_f32_e32 v119, 0x3fb8aa3b, v119
	v_exp_f32_e32 v165, v119
	s_add_i32 s30, s29, 10
	v_add_u32_e32 v119, s30, v118
	v_cvt_f32_u32_e32 v119, v119
	v_fmamk_f32 v119, v119, 0xbc83298c, v120
	v_mul_f32_e64 v119, v117, |v119|
	v_mul_f32_e32 v119, 0x3fb8aa3b, v119
	v_exp_f32_e32 v166, v119
	s_add_i32 s30, s29, 11
	v_add_u32_e32 v119, s30, v118
	v_cvt_f32_u32_e32 v119, v119
	v_fmamk_f32 v119, v119, 0xbc83298c, v120
	v_mul_f32_e64 v119, v117, |v119|
	v_mul_f32_e32 v119, 0x3fb8aa3b, v119
	v_exp_f32_e32 v167, v119
	s_add_i32 s30, s29, 16
	v_add_u32_e32 v119, s30, v118
	v_cvt_f32_u32_e32 v119, v119
	v_fmamk_f32 v119, v119, 0xbc83298c, v120
	v_mul_f32_e64 v119, v117, |v119|
	v_mul_f32_e32 v119, 0x3fb8aa3b, v119
	v_exp_f32_e32 v168, v119
	s_add_i32 s30, s29, 17
	v_add_u32_e32 v119, s30, v118
	v_cvt_f32_u32_e32 v119, v119
	v_fmamk_f32 v119, v119, 0xbc83298c, v120
	v_mul_f32_e64 v119, v117, |v119|
	v_mul_f32_e32 v119, 0x3fb8aa3b, v119
	v_exp_f32_e32 v169, v119
	s_add_i32 s30, s29, 18
	v_add_u32_e32 v119, s30, v118
	v_cvt_f32_u32_e32 v119, v119
	v_fmamk_f32 v119, v119, 0xbc83298c, v120
	v_mul_f32_e64 v119, v117, |v119|
	v_mul_f32_e32 v119, 0x3fb8aa3b, v119
	v_exp_f32_e32 v170, v119
	s_add_i32 s30, s29, 19
	v_add_u32_e32 v119, s30, v118
	v_cvt_f32_u32_e32 v119, v119
	v_fmamk_f32 v119, v119, 0xbc83298c, v120
	v_mul_f32_e64 v119, v117, |v119|
	v_mul_f32_e32 v119, 0x3fb8aa3b, v119
	v_exp_f32_e32 v171, v119
	s_add_i32 s30, s29, 24
	v_add_u32_e32 v119, s30, v118
	v_cvt_f32_u32_e32 v119, v119
	v_fmamk_f32 v119, v119, 0xbc83298c, v120
	v_mul_f32_e64 v119, v117, |v119|
	v_mul_f32_e32 v119, 0x3fb8aa3b, v119
	v_exp_f32_e32 v172, v119
	s_add_i32 s30, s29, 25
	v_add_u32_e32 v119, s30, v118
	v_cvt_f32_u32_e32 v119, v119
	v_fmamk_f32 v119, v119, 0xbc83298c, v120
	v_mul_f32_e64 v119, v117, |v119|
	v_mul_f32_e32 v119, 0x3fb8aa3b, v119
	v_exp_f32_e32 v173, v119
	s_add_i32 s30, s29, 26
	v_add_u32_e32 v119, s30, v118
	v_cvt_f32_u32_e32 v119, v119
	v_fmamk_f32 v119, v119, 0xbc83298c, v120
	v_mul_f32_e64 v119, v117, |v119|
	v_mul_f32_e32 v119, 0x3fb8aa3b, v119
	v_exp_f32_e32 v174, v119
	s_add_i32 s30, s29, 27
	v_add_u32_e32 v119, s30, v118
	v_cvt_f32_u32_e32 v119, v119
	v_fmamk_f32 v119, v119, 0xbc83298c, v120
	v_mul_f32_e64 v119, v117, |v119|
	v_mul_f32_e32 v119, 0x3fb8aa3b, v119
	v_exp_f32_e32 v175, v119
	s_nop 7
	v_mul_f32_e32 v176, v96, v160
	s_mov_b64 s[36:37], s[34:35]
	global_store_dword v115, v176, s[36:37]
	v_mul_f32_e32 v177, v97, v161
	s_add_u32 s36, s34, 0xc000
	s_addc_u32 s37, s35, 0
	global_store_dword v115, v177, s[36:37]
	v_mul_f32_e32 v178, v98, v162
; __device__ __forceinline__ void kraw_items(const Args& a, int gw, int NGW, int lane) {
;     ...
;             const float* wr = a.in[I_FWOUT] + lane * 1536 + c0 + 12 * cb;
;             const f32x4 w0 = *(const f32x4*)(wr), w1 = *(const f32x4*)(wr + 4), w2 = *(const f32x4*)(wr + 8);
;             float wv[12] = {w0.x, w0.y, w0.z, w0.w, w1.x, w1.y, w1.z, w1.w, w2.x, w2.y, w2.z, w2.w};
; #pragma unroll
;             for (int ci = 0; ci < 12; ++ci) { const int c = c0 + 12 * cb + ci;
;                 float acc = 0.f;
; #pragma unroll
;                 for (int jj = 0; jj < 64; ++jj) acc += h[jj] * __builtin_bit_cast(float, __builtin_amdgcn_readlane(__builtin_bit_cast(int, wv[ci]), jj));
;                 const int cm = c % 768;
;                 const float delta = fabsf(-3.0701134573253945f + (float)cm * ((-15.350567286626973f + 3.0701134573253945f) / 767.0f));
;                 KR[(size_t)c * (LP + LS) + p] = acc * __expf(-tt * delta); }
	s_add_u32 s36, s34, 0x18000
	s_addc_u32 s37, s35, 0
	global_store_dword v115, v178, s[36:37]
	v_mul_f32_e32 v179, v99, v163
	s_add_u32 s36, s34, 0x24000
	s_addc_u32 s37, s35, 0
	global_store_dword v115, v179, s[36:37]
	v_mul_f32_e32 v180, v100, v164
	s_add_u32 s36, s34, 0x60000
	s_addc_u32 s37, s35, 0
	global_store_dword v115, v180, s[36:37]
	v_mul_f32_e32 v181, v101, v165
	s_add_u32 s36, s34, 0x6c000
	s_addc_u32 s37, s35, 0
	global_store_dword v115, v181, s[36:37]
	v_mul_f32_e32 v182, v102, v166
	s_add_u32 s36, s34, 0x78000
	s_addc_u32 s37, s35, 0
	global_store_dword v115, v182, s[36:37]
	v_mul_f32_e32 v183, v103, v167
	s_add_u32 s36, s34, 0x84000
	s_addc_u32 s37, s35, 0
	global_store_dword v115, v183, s[36:37]
	v_mul_f32_e32 v184, v104, v168
	s_add_u32 s36, s34, 0xc0000
	s_addc_u32 s37, s35, 0
	global_store_dword v115, v184, s[36:37]
	v_mul_f32_e32 v185, v105, v169
	s_add_u32 s36, s34, 0xcc000
	s_addc_u32 s37, s35, 0
	global_store_dword v115, v185, s[36:37]
	v_mul_f32_e32 v186, v106, v170
	s_add_u32 s36, s34, 0xd8000
	s_addc_u32 s37, s35, 0
	global_store_dword v115, v186, s[36:37]
	v_mul_f32_e32 v187, v107, v171
	s_add_u32 s36, s34, 0xe4000
	s_addc_u32 s37, s35, 0
	global_store_dword v115, v187, s[36:37]
	v_mul_f32_e32 v188, v108, v172
	s_add_u32 s36, s34, 0x120000
	s_addc_u32 s37, s35, 0
	global_store_dword v115, v188, s[36:37]
	v_mul_f32_e32 v189, v109, v173
	s_add_u32 s36, s34, 0x12c000
	s_addc_u32 s37, s35, 0
	global_store_dword v115, v189, s[36:37]
	v_mul_f32_e32 v190, v110, v174
	s_add_u32 s36, s34, 0x138000
	s_addc_u32 s37, s35, 0
	global_store_dword v115, v190, s[36:37]
	v_mul_f32_e32 v191, v111, v175
	s_add_u32 s36, s34, 0x144000
	s_addc_u32 s37, s35, 0
	global_store_dword v115, v191, s[36:37]
	s_add_i32 s28, s21, 32
	s_sub_i32 s29, s28, 0x300
	s_cmp_ge_u32 s28, 0x300
	s_cselect_b32 s29, s29, s28
	s_mul_i32 s30, s28, 0xc000
	s_lshl_b32 s35, s20, 2
	s_add_u32 s30, s30, s35
	s_add_u32 s34, s14, s30
	s_addc_u32 s35, s15, 0
	s_add_i32 s30, s21, 64
	s_lshl_b32 s30, s30, 2
	s_add_u32 s26, s6, s30
	s_addc_u32 s27, s7, 0
	global_load_dword v128, v115, s[26:27]
	s_add_u32 s26, s26, 0x1800
	s_addc_u32 s27, s27, 0
	global_load_dword v129, v115, s[26:27]
	s_add_u32 s26, s26, 0x1800
	s_addc_u32 s27, s27, 0
	global_load_dword v130, v115, s[26:27]
	s_add_u32 s26, s26, 0x1800
	s_addc_u32 s27, s27, 0
	global_load_dword v131, v115, s[26:27]
	s_add_u32 s26, s26, 0x1800
	s_addc_u32 s27, s27, 0
	global_load_dword v132, v115, s[26:27]
	s_add_u32 s26, s26, 0x1800
	s_addc_u32 s27, s27, 0
	global_load_dword v133, v115, s[26:27]
	s_add_u32 s26, s26, 0x1800
	s_addc_u32 s27, s27, 0
	global_load_dword v134, v115, s[26:27]
	s_add_u32 s26, s26, 0x1800
	s_addc_u32 s27, s27, 0
	global_load_dword v135, v115, s[26:27]
	s_add_u32 s26, s26, 0x1800
	s_addc_u32 s27, s27, 0
	global_load_dword v136, v115, s[26:27]
	s_add_u32 s26, s26, 0x1800
	s_addc_u32 s27, s27, 0
	global_load_dword v137, v115, s[26:27]
	s_add_u32 s26, s26, 0x1800
	s_addc_u32 s27, s27, 0
	global_load_dword v138, v115, s[26:27]
	s_add_u32 s26, s26, 0x1800
	s_addc_u32 s27, s27, 0
	global_load_dword v139, v115, s[26:27]
	s_add_u32 s26, s26, 0x1800
	s_addc_u32 s27, s27, 0
	global_load_dword v140, v115, s[26:27]
	s_add_u32 s26, s26, 0x1800
	s_addc_u32 s27, s27, 0
	global_load_dword v141, v115, s[26:27]
	s_add_u32 s26, s26, 0x1800
	s_addc_u32 s27, s27, 0
	global_load_dword v142, v115, s[26:27]
	s_add_u32 s26, s26, 0x1800
	s_addc_u32 s27, s27, 0
	global_load_dword v143, v115, s[26:27]
	s_add_u32 s26, s26, 0x1800
	s_addc_u32 s27, s27, 0
	global_load_dword v144, v115, s[26:27]
	s_add_u32 s26, s26, 0x1800
	s_addc_u32 s27, s27, 0
	global_load_dword v145, v115, s[26:27]
	s_add_u32 s26, s26, 0x1800
	s_addc_u32 s27, s27, 0
	global_load_dword v146, v115, s[26:27]
	s_add_u32 s26, s26, 0x1800
	s_addc_u32 s27, s27, 0
	global_load_dword v147, v115, s[26:27]
	s_add_u32 s26, s26, 0x1800
	s_addc_u32 s27, s27, 0
	global_load_dword v148, v115, s[26:27]
	s_add_u32 s26, s26, 0x1800
	s_addc_u32 s27, s27, 0
	global_load_dword v149, v115, s[26:27]
	s_add_u32 s26, s26, 0x1800
	s_addc_u32 s27, s27, 0
	global_load_dword v150, v115, s[26:27]
	s_add_u32 s26, s26, 0x1800
	s_addc_u32 s27, s27, 0
	global_load_dword v151, v115, s[26:27]
	s_add_u32 s26, s26, 0x1800
	s_addc_u32 s27, s27, 0
	global_load_dword v152, v115, s[26:27]
	s_add_u32 s26, s26, 0x1800
	s_addc_u32 s27, s27, 0
	global_load_dword v153, v115, s[26:27]
	s_add_u32 s26, s26, 0x1800
	s_addc_u32 s27, s27, 0
	global_load_dword v154, v115, s[26:27]
	s_add_u32 s26, s26, 0x1800
	s_addc_u32 s27, s27, 0
	global_load_dword v155, v115, s[26:27]
	s_add_u32 s26, s26, 0x1800
	s_addc_u32 s27, s27, 0
	global_load_dword v156, v115, s[26:27]
	s_add_u32 s26, s26, 0x1800
	s_addc_u32 s27, s27, 0
	global_load_dword v157, v115, s[26:27]
	s_add_u32 s26, s26, 0x1800
	s_addc_u32 s27, s27, 0
	global_load_dword v158, v115, s[26:27]
	s_add_u32 s26, s26, 0x1800
	s_addc_u32 s27, s27, 0
	global_load_dword v159, v115, s[26:27]
	s_waitcnt vmcnt(48)
; __device__ __forceinline__ void kraw_items(const Args& a, int gw, int NGW, int lane) {
;     ...
;             for (int ci = 0; ci < 12; ++ci) { const int c = c0 + 12 * cb + ci;
;                 float acc = 0.f;
; #pragma unroll
;                 for (int jj = 0; jj < 64; ++jj) acc += h[jj] * __builtin_bit_cast(float, __builtin_amdgcn_readlane(__builtin_bit_cast(int, wv[ci]), jj));
;                 const int cm = c % 768;
;                 const float delta = fabsf(-3.0701134573253945f + (float)cm * ((-15.350567286626973f + 3.0701134573253945f) / 767.0f));
;                 KR[(size_t)c * (LP + LS) + p] = acc * __expf(-tt * delta); }
	v_mfma_f32_32x32x2_f32 v[96:111], v64, v32, 0
	v_mfma_f32_32x32x2_f32 v[96:111], v65, v33, v[96:111]
	v_mfma_f32_32x32x2_f32 v[96:111], v66, v34, v[96:111]
	v_mfma_f32_32x32x2_f32 v[96:111], v67, v35, v[96:111]
	v_mfma_f32_32x32x2_f32 v[96:111], v68, v36, v[96:111]
	v_mfma_f32_32x32x2_f32 v[96:111], v69, v37, v[96:111]
	v_mfma_f32_32x32x2_f32 v[96:111], v70, v38, v[96:111]
	v_mfma_f32_32x32x2_f32 v[96:111], v71, v39, v[96:111]
	v_mfma_f32_32x32x2_f32 v[96:111], v72, v40, v[96:111]
	v_mfma_f32_32x32x2_f32 v[96:111], v73, v41, v[96:111]
	v_mfma_f32_32x32x2_f32 v[96:111], v74, v42, v[96:111]
	v_mfma_f32_32x32x2_f32 v[96:111], v75, v43, v[96:111]
	v_mfma_f32_32x32x2_f32 v[96:111], v76, v44, v[96:111]
	v_mfma_f32_32x32x2_f32 v[96:111], v77, v45, v[96:111]
	v_mfma_f32_32x32x2_f32 v[96:111], v78, v46, v[96:111]
	v_mfma_f32_32x32x2_f32 v[96:111], v79, v47, v[96:111]
	v_mfma_f32_32x32x2_f32 v[96:111], v80, v48, v[96:111]
	v_mfma_f32_32x32x2_f32 v[96:111], v81, v49, v[96:111]
	v_mfma_f32_32x32x2_f32 v[96:111], v82, v50, v[96:111]
	v_mfma_f32_32x32x2_f32 v[96:111], v83, v51, v[96:111]
	v_mfma_f32_32x32x2_f32 v[96:111], v84, v52, v[96:111]
	v_mfma_f32_32x32x2_f32 v[96:111], v85, v53, v[96:111]
	v_mfma_f32_32x32x2_f32 v[96:111], v86, v54, v[96:111]
	v_mfma_f32_32x32x2_f32 v[96:111], v87, v55, v[96:111]
	v_mfma_f32_32x32x2_f32 v[96:111], v88, v56, v[96:111]
	v_mfma_f32_32x32x2_f32 v[96:111], v89, v57, v[96:111]
	v_mfma_f32_32x32x2_f32 v[96:111], v90, v58, v[96:111]
	v_mfma_f32_32x32x2_f32 v[96:111], v91, v59, v[96:111]
	v_mfma_f32_32x32x2_f32 v[96:111], v92, v60, v[96:111]
	v_mfma_f32_32x32x2_f32 v[96:111], v93, v61, v[96:111]
	v_mfma_f32_32x32x2_f32 v[96:111], v94, v62, v[96:111]
	v_mfma_f32_32x32x2_f32 v[96:111], v95, v63, v[96:111]
	s_add_i32 s30, s29, 0
	v_add_u32_e32 v119, s30, v118
	v_cvt_f32_u32_e32 v119, v119
	v_fmamk_f32 v119, v119, 0xbc83298c, v120
	v_mul_f32_e64 v119, v117, |v119|
	v_mul_f32_e32 v119, 0x3fb8aa3b, v119
	v_exp_f32_e32 v160, v119
	s_add_i32 s30, s29, 1
	v_add_u32_e32 v119, s30, v118
	v_cvt_f32_u32_e32 v119, v119
	v_fmamk_f32 v119, v119, 0xbc83298c, v120
	v_mul_f32_e64 v119, v117, |v119|
	v_mul_f32_e32 v119, 0x3fb8aa3b, v119
	v_exp_f32_e32 v161, v119
	s_add_i32 s30, s29, 2
	v_add_u32_e32 v119, s30, v118
	v_cvt_f32_u32_e32 v119, v119
	v_fmamk_f32 v119, v119, 0xbc83298c, v120
	v_mul_f32_e64 v119, v117, |v119|
	v_mul_f32_e32 v119, 0x3fb8aa3b, v119
	v_exp_f32_e32 v162, v119
	s_add_i32 s30, s29, 3
	v_add_u32_e32 v119, s30, v118
	v_cvt_f32_u32_e32 v119, v119
	v_fmamk_f32 v119, v119, 0xbc83298c, v120
	v_mul_f32_e64 v119, v117, |v119|
	v_mul_f32_e32 v119, 0x3fb8aa3b, v119
	v_exp_f32_e32 v163, v119
	s_add_i32 s30, s29, 8
	v_add_u32_e32 v119, s30, v118
	v_cvt_f32_u32_e32 v119, v119
	v_fmamk_f32 v119, v119, 0xbc83298c, v120
	v_mul_f32_e64 v119, v117, |v119|
	v_mul_f32_e32 v119, 0x3fb8aa3b, v119
	v_exp_f32_e32 v164, v119
	s_add_i32 s30, s29, 9
	v_add_u32_e32 v119, s30, v118
	v_cvt_f32_u32_e32 v119, v119
	v_fmamk_f32 v119, v119, 0xbc83298c, v120
	v_mul_f32_e64 v119, v117, |v119|
	v_mul_f32_e32 v119, 0x3fb8aa3b, v119
	v_exp_f32_e32 v165, v119
	s_add_i32 s30, s29, 10
	v_add_u32_e32 v119, s30, v118
	v_cvt_f32_u32_e32 v119, v119
	v_fmamk_f32 v119, v119, 0xbc83298c, v120
	v_mul_f32_e64 v119, v117, |v119|
	v_mul_f32_e32 v119, 0x3fb8aa3b, v119
	v_exp_f32_e32 v166, v119
	s_add_i32 s30, s29, 11
	v_add_u32_e32 v119, s30, v118
	v_cvt_f32_u32_e32 v119, v119
	v_fmamk_f32 v119, v119, 0xbc83298c, v120
	v_mul_f32_e64 v119, v117, |v119|
	v_mul_f32_e32 v119, 0x3fb8aa3b, v119
	v_exp_f32_e32 v167, v119
	s_add_i32 s30, s29, 16
	v_add_u32_e32 v119, s30, v118
	v_cvt_f32_u32_e32 v119, v119
	v_fmamk_f32 v119, v119, 0xbc83298c, v120
	v_mul_f32_e64 v119, v117, |v119|
	v_mul_f32_e32 v119, 0x3fb8aa3b, v119
	v_exp_f32_e32 v168, v119
	s_add_i32 s30, s29, 17
	v_add_u32_e32 v119, s30, v118
	v_cvt_f32_u32_e32 v119, v119
	v_fmamk_f32 v119, v119, 0xbc83298c, v120
	v_mul_f32_e64 v119, v117, |v119|
	v_mul_f32_e32 v119, 0x3fb8aa3b, v119
	v_exp_f32_e32 v169, v119
	s_add_i32 s30, s29, 18
	v_add_u32_e32 v119, s30, v118
	v_cvt_f32_u32_e32 v119, v119
	v_fmamk_f32 v119, v119, 0xbc83298c, v120
	v_mul_f32_e64 v119, v117, |v119|
	v_mul_f32_e32 v119, 0x3fb8aa3b, v119
	v_exp_f32_e32 v170, v119
	s_add_i32 s30, s29, 19
	v_add_u32_e32 v119, s30, v118
	v_cvt_f32_u32_e32 v119, v119
	v_fmamk_f32 v119, v119, 0xbc83298c, v120
	v_mul_f32_e64 v119, v117, |v119|
	v_mul_f32_e32 v119, 0x3fb8aa3b, v119
	v_exp_f32_e32 v171, v119
	s_add_i32 s30, s29, 24
	v_add_u32_e32 v119, s30, v118
	v_cvt_f32_u32_e32 v119, v119
	v_fmamk_f32 v119, v119, 0xbc83298c, v120
	v_mul_f32_e64 v119, v117, |v119|
	v_mul_f32_e32 v119, 0x3fb8aa3b, v119
	v_exp_f32_e32 v172, v119
	s_add_i32 s30, s29, 25
	v_add_u32_e32 v119, s30, v118
	v_cvt_f32_u32_e32 v119, v119
	v_fmamk_f32 v119, v119, 0xbc83298c, v120
	v_mul_f32_e64 v119, v117, |v119|
	v_mul_f32_e32 v119, 0x3fb8aa3b, v119
	v_exp_f32_e32 v173, v119
	s_add_i32 s30, s29, 26
	v_add_u32_e32 v119, s30, v118
	v_cvt_f32_u32_e32 v119, v119
	v_fmamk_f32 v119, v119, 0xbc83298c, v120
	v_mul_f32_e64 v119, v117, |v119|
	v_mul_f32_e32 v119, 0x3fb8aa3b, v119
	v_exp_f32_e32 v174, v119
	s_add_i32 s30, s29, 27
	v_add_u32_e32 v119, s30, v118
	v_cvt_f32_u32_e32 v119, v119
	v_fmamk_f32 v119, v119, 0xbc83298c, v120
	v_mul_f32_e64 v119, v117, |v119|
	v_mul_f32_e32 v119, 0x3fb8aa3b, v119
	v_exp_f32_e32 v175, v119
	s_nop 7
	v_mul_f32_e32 v176, v96, v160
	s_mov_b64 s[36:37], s[34:35]
	global_store_dword v115, v176, s[36:37]
	v_mul_f32_e32 v177, v97, v161
	s_add_u32 s36, s34, 0xc000
	s_addc_u32 s37, s35, 0
	global_store_dword v115, v177, s[36:37]
	v_mul_f32_e32 v178, v98, v162
	s_add_u32 s36, s34, 0x18000
; __device__ __forceinline__ void kraw_items(const Args& a, int gw, int NGW, int lane) {
;     ...
;     for (int it = gw; it < 192 * 32; it += NGW) {
;         const int pg = it >> 5, cgp = it & 31, p = pg * 64 + lane, c0 = cgp * 48;
;         float h[64];
; #pragma unroll
;         for (int q = 0; q < 16; ++q) { const f32x4 t = *(const f32x4*)(H3 + (size_t)p * 64 + 4 * q); h[4 * q] = t.x; h[4 * q + 1] = t.y; h[4 * q + 2] = t.z; h[4 * q + 3] = t.w; }
;         const int grp = p >= LP, tpos = p - grp * LP, L = grp ? LS : LP;
;         const float tt = (float)tpos * (1.0f / (float)(L - 1));
; #pragma unroll 1
;         for (int cb = 0; cb < 4; ++cb) {
;             const float* wr = a.in[I_FWOUT] + lane * 1536 + c0 + 12 * cb;
;             const f32x4 w0 = *(const f32x4*)(wr), w1 = *(const f32x4*)(wr + 4), w2 = *(const f32x4*)(wr + 8);
;             float wv[12] = {w0.x, w0.y, w0.z, w0.w, w1.x, w1.y, w1.z, w1.w, w2.x, w2.y, w2.z, w2.w};
; #pragma unroll
;             for (int ci = 0; ci < 12; ++ci) { const int c = c0 + 12 * cb + ci;
;                 float acc = 0.f;
; #pragma unroll
;                 for (int jj = 0; jj < 64; ++jj) acc += h[jj] * __builtin_bit_cast(float, __builtin_amdgcn_readlane(__builtin_bit_cast(int, wv[ci]), jj));
;                 const int cm = c % 768;
;                 const float delta = fabsf(-3.0701134573253945f + (float)cm * ((-15.350567286626973f + 3.0701134573253945f) / 767.0f));
;                 KR[(size_t)c * (LP + LS) + p] = acc * __expf(-tt * delta); }
	s_addc_u32 s37, s35, 0
	global_store_dword v115, v178, s[36:37]
	v_mul_f32_e32 v179, v99, v163
	s_add_u32 s36, s34, 0x24000
	s_addc_u32 s37, s35, 0
	global_store_dword v115, v179, s[36:37]
	v_mul_f32_e32 v180, v100, v164
	s_add_u32 s36, s34, 0x60000
	s_addc_u32 s37, s35, 0
	global_store_dword v115, v180, s[36:37]
	v_mul_f32_e32 v181, v101, v165
	s_add_u32 s36, s34, 0x6c000
	s_addc_u32 s37, s35, 0
	global_store_dword v115, v181, s[36:37]
	v_mul_f32_e32 v182, v102, v166
	s_add_u32 s36, s34, 0x78000
	s_addc_u32 s37, s35, 0
	global_store_dword v115, v182, s[36:37]
	v_mul_f32_e32 v183, v103, v167
	s_add_u32 s36, s34, 0x84000
	s_addc_u32 s37, s35, 0
	global_store_dword v115, v183, s[36:37]
	v_mul_f32_e32 v184, v104, v168
	s_add_u32 s36, s34, 0xc0000
	s_addc_u32 s37, s35, 0
	global_store_dword v115, v184, s[36:37]
	v_mul_f32_e32 v185, v105, v169
	s_add_u32 s36, s34, 0xcc000
	s_addc_u32 s37, s35, 0
	global_store_dword v115, v185, s[36:37]
	v_mul_f32_e32 v186, v106, v170
	s_add_u32 s36, s34, 0xd8000
	s_addc_u32 s37, s35, 0
	global_store_dword v115, v186, s[36:37]
	v_mul_f32_e32 v187, v107, v171
	s_add_u32 s36, s34, 0xe4000
	s_addc_u32 s37, s35, 0
	global_store_dword v115, v187, s[36:37]
	v_mul_f32_e32 v188, v108, v172
	s_add_u32 s36, s34, 0x120000
	s_addc_u32 s37, s35, 0
	global_store_dword v115, v188, s[36:37]
	v_mul_f32_e32 v189, v109, v173
	s_add_u32 s36, s34, 0x12c000
	s_addc_u32 s37, s35, 0
	global_store_dword v115, v189, s[36:37]
	v_mul_f32_e32 v190, v110, v174
	s_add_u32 s36, s34, 0x138000
	s_addc_u32 s37, s35, 0
	global_store_dword v115, v190, s[36:37]
	v_mul_f32_e32 v191, v111, v175
	s_add_u32 s36, s34, 0x144000
	s_addc_u32 s37, s35, 0
	global_store_dword v115, v191, s[36:37]
	s_add_i32 s28, s21, 64
	s_sub_i32 s29, s28, 0x300
	s_cmp_ge_u32 s28, 0x300
	s_cselect_b32 s29, s29, s28
	s_mul_i32 s30, s28, 0xc000
	s_lshl_b32 s35, s20, 2
	s_add_u32 s30, s30, s35
	s_add_u32 s34, s14, s30
	s_addc_u32 s35, s15, 0
	s_add_i32 s17, s16, 0x1000
	s_lshr_b32 s18, s17, 4
	s_and_b32 s19, s17, 15
	s_lshl_b32 s20, s18, 5
	s_mul_i32 s21, s19, 0x60
	s_lshl_b32 s30, s20, 8
	s_add_u32 s24, s10, s30
	s_addc_u32 s25, s11, 0
	global_load_dwordx4 v[0:3], v114, s[24:25] offset:0
	global_load_dwordx4 v[4:7], v114, s[24:25] offset:16
	global_load_dwordx4 v[8:11], v114, s[24:25] offset:32
	global_load_dwordx4 v[12:15], v114, s[24:25] offset:48
	global_load_dwordx4 v[16:19], v114, s[24:25] offset:64
	global_load_dwordx4 v[20:23], v114, s[24:25] offset:80
	global_load_dwordx4 v[24:27], v114, s[24:25] offset:96
	global_load_dwordx4 v[28:31], v114, s[24:25] offset:112
	s_add_i32 s30, s21, 0
	s_lshl_b32 s30, s30, 2
	s_add_u32 s26, s6, s30
	s_addc_u32 s27, s7, 0
	global_load_dword v64, v115, s[26:27]
	s_add_u32 s26, s26, 0x1800
	s_addc_u32 s27, s27, 0
	global_load_dword v65, v115, s[26:27]
	s_add_u32 s26, s26, 0x1800
	s_addc_u32 s27, s27, 0
	global_load_dword v66, v115, s[26:27]
	s_add_u32 s26, s26, 0x1800
	s_addc_u32 s27, s27, 0
	global_load_dword v67, v115, s[26:27]
	s_add_u32 s26, s26, 0x1800
	s_addc_u32 s27, s27, 0
	global_load_dword v68, v115, s[26:27]
	s_add_u32 s26, s26, 0x1800
	s_addc_u32 s27, s27, 0
	global_load_dword v69, v115, s[26:27]
	s_add_u32 s26, s26, 0x1800
	s_addc_u32 s27, s27, 0
	global_load_dword v70, v115, s[26:27]
	s_add_u32 s26, s26, 0x1800
	s_addc_u32 s27, s27, 0
	global_load_dword v71, v115, s[26:27]
	s_add_u32 s26, s26, 0x1800
	s_addc_u32 s27, s27, 0
	global_load_dword v72, v115, s[26:27]
	s_add_u32 s26, s26, 0x1800
	s_addc_u32 s27, s27, 0
	global_load_dword v73, v115, s[26:27]
	s_add_u32 s26, s26, 0x1800
	s_addc_u32 s27, s27, 0
	global_load_dword v74, v115, s[26:27]
	s_add_u32 s26, s26, 0x1800
	s_addc_u32 s27, s27, 0
	global_load_dword v75, v115, s[26:27]
	s_add_u32 s26, s26, 0x1800
	s_addc_u32 s27, s27, 0
	global_load_dword v76, v115, s[26:27]
	s_add_u32 s26, s26, 0x1800
	s_addc_u32 s27, s27, 0
	global_load_dword v77, v115, s[26:27]
	s_add_u32 s26, s26, 0x1800
	s_addc_u32 s27, s27, 0
	global_load_dword v78, v115, s[26:27]
	s_add_u32 s26, s26, 0x1800
	s_addc_u32 s27, s27, 0
	global_load_dword v79, v115, s[26:27]
	s_add_u32 s26, s26, 0x1800
	s_addc_u32 s27, s27, 0
	global_load_dword v80, v115, s[26:27]
	s_add_u32 s26, s26, 0x1800
	s_addc_u32 s27, s27, 0
	global_load_dword v81, v115, s[26:27]
	s_add_u32 s26, s26, 0x1800
	s_addc_u32 s27, s27, 0
	global_load_dword v82, v115, s[26:27]
	s_add_u32 s26, s26, 0x1800
	s_addc_u32 s27, s27, 0
	global_load_dword v83, v115, s[26:27]
	s_add_u32 s26, s26, 0x1800
	s_addc_u32 s27, s27, 0
	global_load_dword v84, v115, s[26:27]
	s_add_u32 s26, s26, 0x1800
	s_addc_u32 s27, s27, 0
	global_load_dword v85, v115, s[26:27]
	s_add_u32 s26, s26, 0x1800
	s_addc_u32 s27, s27, 0
	global_load_dword v86, v115, s[26:27]
	s_add_u32 s26, s26, 0x1800
	s_addc_u32 s27, s27, 0
	global_load_dword v87, v115, s[26:27]
	s_add_u32 s26, s26, 0x1800
	s_addc_u32 s27, s27, 0
	global_load_dword v88, v115, s[26:27]
	s_add_u32 s26, s26, 0x1800
	s_addc_u32 s27, s27, 0
	global_load_dword v89, v115, s[26:27]
	s_add_u32 s26, s26, 0x1800
	s_addc_u32 s27, s27, 0
	global_load_dword v90, v115, s[26:27]
	s_add_u32 s26, s26, 0x1800
	s_addc_u32 s27, s27, 0
	global_load_dword v91, v115, s[26:27]
	s_add_u32 s26, s26, 0x1800
	s_addc_u32 s27, s27, 0
	global_load_dword v92, v115, s[26:27]
	s_add_u32 s26, s26, 0x1800
	s_addc_u32 s27, s27, 0
	global_load_dword v93, v115, s[26:27]
	s_add_u32 s26, s26, 0x1800
	s_addc_u32 s27, s27, 0
	global_load_dword v94, v115, s[26:27]
	s_add_u32 s26, s26, 0x1800
	s_addc_u32 s27, s27, 0
	global_load_dword v95, v115, s[26:27]
	s_waitcnt vmcnt(56)
; __device__ __forceinline__ void kraw_items(const Args& a, int gw, int NGW, int lane) {
;     ...
;             for (int ci = 0; ci < 12; ++ci) { const int c = c0 + 12 * cb + ci;
;                 float acc = 0.f;
; #pragma unroll
;                 for (int jj = 0; jj < 64; ++jj) acc += h[jj] * __builtin_bit_cast(float, __builtin_amdgcn_readlane(__builtin_bit_cast(int, wv[ci]), jj));
;                 const int cm = c % 768;
;                 const float delta = fabsf(-3.0701134573253945f + (float)cm * ((-15.350567286626973f + 3.0701134573253945f) / 767.0f));
;                 KR[(size_t)c * (LP + LS) + p] = acc * __expf(-tt * delta); }
	v_mfma_f32_32x32x2_f32 v[96:111], v128, v32, 0
	v_mfma_f32_32x32x2_f32 v[96:111], v129, v33, v[96:111]
	v_mfma_f32_32x32x2_f32 v[96:111], v130, v34, v[96:111]
	v_mfma_f32_32x32x2_f32 v[96:111], v131, v35, v[96:111]
	v_mfma_f32_32x32x2_f32 v[96:111], v132, v36, v[96:111]
	v_mfma_f32_32x32x2_f32 v[96:111], v133, v37, v[96:111]
	v_mfma_f32_32x32x2_f32 v[96:111], v134, v38, v[96:111]
	v_mfma_f32_32x32x2_f32 v[96:111], v135, v39, v[96:111]
	v_mfma_f32_32x32x2_f32 v[96:111], v136, v40, v[96:111]
	v_mfma_f32_32x32x2_f32 v[96:111], v137, v41, v[96:111]
	v_mfma_f32_32x32x2_f32 v[96:111], v138, v42, v[96:111]
	v_mfma_f32_32x32x2_f32 v[96:111], v139, v43, v[96:111]
	v_mfma_f32_32x32x2_f32 v[96:111], v140, v44, v[96:111]
	v_mfma_f32_32x32x2_f32 v[96:111], v141, v45, v[96:111]
	v_mfma_f32_32x32x2_f32 v[96:111], v142, v46, v[96:111]
	v_mfma_f32_32x32x2_f32 v[96:111], v143, v47, v[96:111]
	v_mfma_f32_32x32x2_f32 v[96:111], v144, v48, v[96:111]
	v_mfma_f32_32x32x2_f32 v[96:111], v145, v49, v[96:111]
	v_mfma_f32_32x32x2_f32 v[96:111], v146, v50, v[96:111]
	v_mfma_f32_32x32x2_f32 v[96:111], v147, v51, v[96:111]
	v_mfma_f32_32x32x2_f32 v[96:111], v148, v52, v[96:111]
	v_mfma_f32_32x32x2_f32 v[96:111], v149, v53, v[96:111]
	v_mfma_f32_32x32x2_f32 v[96:111], v150, v54, v[96:111]
	v_mfma_f32_32x32x2_f32 v[96:111], v151, v55, v[96:111]
	v_mfma_f32_32x32x2_f32 v[96:111], v152, v56, v[96:111]
	v_mfma_f32_32x32x2_f32 v[96:111], v153, v57, v[96:111]
	v_mfma_f32_32x32x2_f32 v[96:111], v154, v58, v[96:111]
	v_mfma_f32_32x32x2_f32 v[96:111], v155, v59, v[96:111]
	v_mfma_f32_32x32x2_f32 v[96:111], v156, v60, v[96:111]
	v_mfma_f32_32x32x2_f32 v[96:111], v157, v61, v[96:111]
	v_mfma_f32_32x32x2_f32 v[96:111], v158, v62, v[96:111]
	v_mfma_f32_32x32x2_f32 v[96:111], v159, v63, v[96:111]
	s_add_i32 s30, s29, 0
	v_add_u32_e32 v119, s30, v118
	v_cvt_f32_u32_e32 v119, v119
	v_fmamk_f32 v119, v119, 0xbc83298c, v120
	v_mul_f32_e64 v119, v117, |v119|
	v_mul_f32_e32 v119, 0x3fb8aa3b, v119
	v_exp_f32_e32 v160, v119
	s_add_i32 s30, s29, 1
	v_add_u32_e32 v119, s30, v118
	v_cvt_f32_u32_e32 v119, v119
	v_fmamk_f32 v119, v119, 0xbc83298c, v120
	v_mul_f32_e64 v119, v117, |v119|
	v_mul_f32_e32 v119, 0x3fb8aa3b, v119
	v_exp_f32_e32 v161, v119
	s_add_i32 s30, s29, 2
	v_add_u32_e32 v119, s30, v118
	v_cvt_f32_u32_e32 v119, v119
	v_fmamk_f32 v119, v119, 0xbc83298c, v120
	v_mul_f32_e64 v119, v117, |v119|
	v_mul_f32_e32 v119, 0x3fb8aa3b, v119
	v_exp_f32_e32 v162, v119
	s_add_i32 s30, s29, 3
	v_add_u32_e32 v119, s30, v118
	v_cvt_f32_u32_e32 v119, v119
	v_fmamk_f32 v119, v119, 0xbc83298c, v120
	v_mul_f32_e64 v119, v117, |v119|
	v_mul_f32_e32 v119, 0x3fb8aa3b, v119
	v_exp_f32_e32 v163, v119
	s_add_i32 s30, s29, 8
	v_add_u32_e32 v119, s30, v118
	v_cvt_f32_u32_e32 v119, v119
	v_fmamk_f32 v119, v119, 0xbc83298c, v120
	v_mul_f32_e64 v119, v117, |v119|
	v_mul_f32_e32 v119, 0x3fb8aa3b, v119
	v_exp_f32_e32 v164, v119
	s_add_i32 s30, s29, 9
	v_add_u32_e32 v119, s30, v118
	v_cvt_f32_u32_e32 v119, v119
	v_fmamk_f32 v119, v119, 0xbc83298c, v120
	v_mul_f32_e64 v119, v117, |v119|
	v_mul_f32_e32 v119, 0x3fb8aa3b, v119
	v_exp_f32_e32 v165, v119
	s_add_i32 s30, s29, 10
	v_add_u32_e32 v119, s30, v118
	v_cvt_f32_u32_e32 v119, v119
	v_fmamk_f32 v119, v119, 0xbc83298c, v120
	v_mul_f32_e64 v119, v117, |v119|
	v_mul_f32_e32 v119, 0x3fb8aa3b, v119
	v_exp_f32_e32 v166, v119
	s_add_i32 s30, s29, 11
	v_add_u32_e32 v119, s30, v118
	v_cvt_f32_u32_e32 v119, v119
	v_fmamk_f32 v119, v119, 0xbc83298c, v120
	v_mul_f32_e64 v119, v117, |v119|
	v_mul_f32_e32 v119, 0x3fb8aa3b, v119
	v_exp_f32_e32 v167, v119
	s_add_i32 s30, s29, 16
	v_add_u32_e32 v119, s30, v118
	v_cvt_f32_u32_e32 v119, v119
	v_fmamk_f32 v119, v119, 0xbc83298c, v120
	v_mul_f32_e64 v119, v117, |v119|
	v_mul_f32_e32 v119, 0x3fb8aa3b, v119
	v_exp_f32_e32 v168, v119
	s_add_i32 s30, s29, 17
	v_add_u32_e32 v119, s30, v118
	v_cvt_f32_u32_e32 v119, v119
	v_fmamk_f32 v119, v119, 0xbc83298c, v120
	v_mul_f32_e64 v119, v117, |v119|
	v_mul_f32_e32 v119, 0x3fb8aa3b, v119
	v_exp_f32_e32 v169, v119
	s_add_i32 s30, s29, 18
	v_add_u32_e32 v119, s30, v118
	v_cvt_f32_u32_e32 v119, v119
	v_fmamk_f32 v119, v119, 0xbc83298c, v120
	v_mul_f32_e64 v119, v117, |v119|
	v_mul_f32_e32 v119, 0x3fb8aa3b, v119
	v_exp_f32_e32 v170, v119
	s_add_i32 s30, s29, 19
	v_add_u32_e32 v119, s30, v118
	v_cvt_f32_u32_e32 v119, v119
	v_fmamk_f32 v119, v119, 0xbc83298c, v120
	v_mul_f32_e64 v119, v117, |v119|
	v_mul_f32_e32 v119, 0x3fb8aa3b, v119
	v_exp_f32_e32 v171, v119
	s_add_i32 s30, s29, 24
	v_add_u32_e32 v119, s30, v118
	v_cvt_f32_u32_e32 v119, v119
	v_fmamk_f32 v119, v119, 0xbc83298c, v120
	v_mul_f32_e64 v119, v117, |v119|
	v_mul_f32_e32 v119, 0x3fb8aa3b, v119
	v_exp_f32_e32 v172, v119
	s_add_i32 s30, s29, 25
	v_add_u32_e32 v119, s30, v118
	v_cvt_f32_u32_e32 v119, v119
	v_fmamk_f32 v119, v119, 0xbc83298c, v120
	v_mul_f32_e64 v119, v117, |v119|
	v_mul_f32_e32 v119, 0x3fb8aa3b, v119
	v_exp_f32_e32 v173, v119
	s_add_i32 s30, s29, 26
	v_add_u32_e32 v119, s30, v118
	v_cvt_f32_u32_e32 v119, v119
	v_fmamk_f32 v119, v119, 0xbc83298c, v120
	v_mul_f32_e64 v119, v117, |v119|
	v_mul_f32_e32 v119, 0x3fb8aa3b, v119
	v_exp_f32_e32 v174, v119
	s_add_i32 s30, s29, 27
	v_add_u32_e32 v119, s30, v118
	v_cvt_f32_u32_e32 v119, v119
	v_fmamk_f32 v119, v119, 0xbc83298c, v120
	v_mul_f32_e64 v119, v117, |v119|
	v_mul_f32_e32 v119, 0x3fb8aa3b, v119
	v_exp_f32_e32 v175, v119
	s_nop 7
	v_mul_f32_e32 v176, v96, v160
	s_mov_b64 s[36:37], s[34:35]
	global_store_dword v115, v176, s[36:37]
	v_mul_f32_e32 v177, v97, v161
	s_add_u32 s36, s34, 0xc000
	s_addc_u32 s37, s35, 0
	global_store_dword v115, v177, s[36:37]
	v_mul_f32_e32 v178, v98, v162
; __device__ __forceinline__ void kraw_items(const Args& a, int gw, int NGW, int lane) {
;     ...
;         const int grp = p >= LP, tpos = p - grp * LP, L = grp ? LS : LP;
;         const float tt = (float)tpos * (1.0f / (float)(L - 1));
; #pragma unroll 1
;         for (int cb = 0; cb < 4; ++cb) {
;             const float* wr = a.in[I_FWOUT] + lane * 1536 + c0 + 12 * cb;
;             const f32x4 w0 = *(const f32x4*)(wr), w1 = *(const f32x4*)(wr + 4), w2 = *(const f32x4*)(wr + 8);
;             float wv[12] = {w0.x, w0.y, w0.z, w0.w, w1.x, w1.y, w1.z, w1.w, w2.x, w2.y, w2.z, w2.w};
; #pragma unroll
;             for (int ci = 0; ci < 12; ++ci) { const int c = c0 + 12 * cb + ci;
;                 float acc = 0.f;
; #pragma unroll
;                 for (int jj = 0; jj < 64; ++jj) acc += h[jj] * __builtin_bit_cast(float, __builtin_amdgcn_readlane(__builtin_bit_cast(int, wv[ci]), jj));
;                 const int cm = c % 768;
;                 const float delta = fabsf(-3.0701134573253945f + (float)cm * ((-15.350567286626973f + 3.0701134573253945f) / 767.0f));
;                 KR[(size_t)c * (LP + LS) + p] = acc * __expf(-tt * delta); }
	s_add_u32 s36, s34, 0x18000
	s_addc_u32 s37, s35, 0
	global_store_dword v115, v178, s[36:37]
	v_mul_f32_e32 v179, v99, v163
	s_add_u32 s36, s34, 0x24000
	s_addc_u32 s37, s35, 0
	global_store_dword v115, v179, s[36:37]
	v_mul_f32_e32 v180, v100, v164
	s_add_u32 s36, s34, 0x60000
	s_addc_u32 s37, s35, 0
	global_store_dword v115, v180, s[36:37]
	v_mul_f32_e32 v181, v101, v165
	s_add_u32 s36, s34, 0x6c000
	s_addc_u32 s37, s35, 0
	global_store_dword v115, v181, s[36:37]
	v_mul_f32_e32 v182, v102, v166
	s_add_u32 s36, s34, 0x78000
	s_addc_u32 s37, s35, 0
	global_store_dword v115, v182, s[36:37]
	v_mul_f32_e32 v183, v103, v167
	s_add_u32 s36, s34, 0x84000
	s_addc_u32 s37, s35, 0
	global_store_dword v115, v183, s[36:37]
	v_mul_f32_e32 v184, v104, v168
	s_add_u32 s36, s34, 0xc0000
	s_addc_u32 s37, s35, 0
	global_store_dword v115, v184, s[36:37]
	v_mul_f32_e32 v185, v105, v169
	s_add_u32 s36, s34, 0xcc000
	s_addc_u32 s37, s35, 0
	global_store_dword v115, v185, s[36:37]
	v_mul_f32_e32 v186, v106, v170
	s_add_u32 s36, s34, 0xd8000
	s_addc_u32 s37, s35, 0
	global_store_dword v115, v186, s[36:37]
	v_mul_f32_e32 v187, v107, v171
	s_add_u32 s36, s34, 0xe4000
	s_addc_u32 s37, s35, 0
	global_store_dword v115, v187, s[36:37]
	v_mul_f32_e32 v188, v108, v172
	s_add_u32 s36, s34, 0x120000
	s_addc_u32 s37, s35, 0
	global_store_dword v115, v188, s[36:37]
	v_mul_f32_e32 v189, v109, v173
	s_add_u32 s36, s34, 0x12c000
	s_addc_u32 s37, s35, 0
	global_store_dword v115, v189, s[36:37]
	v_mul_f32_e32 v190, v110, v174
	s_add_u32 s36, s34, 0x138000
	s_addc_u32 s37, s35, 0
	global_store_dword v115, v190, s[36:37]
	v_mul_f32_e32 v191, v111, v175
	s_add_u32 s36, s34, 0x144000
	s_addc_u32 s37, s35, 0
	global_store_dword v115, v191, s[36:37]
	s_add_i32 s28, s21, 0
	s_sub_i32 s29, s28, 0x300
	s_cmp_ge_u32 s28, 0x300
	s_cselect_b32 s29, s29, s28
	s_mul_i32 s30, s28, 0xc000
	s_lshl_b32 s35, s20, 2
	s_add_u32 s30, s30, s35
	s_add_u32 s34, s14, s30
	s_addc_u32 s35, s15, 0
	s_mov_b32 s22, 0xb9000400
	s_cmp_ge_u32 s20, 0x2000
	s_cselect_b32 s22, 0xb9800801, s22
	s_and_b32 s30, s20, 0x1fff
	v_add_u32_e32 v119, s30, v112
	v_cvt_f32_u32_e32 v119, v119
	v_mul_f32_e32 v117, s22, v119
	s_add_i32 s30, s21, 32
	s_lshl_b32 s30, s30, 2
	s_add_u32 s26, s6, s30
	s_addc_u32 s27, s7, 0
	global_load_dword v128, v115, s[26:27]
	s_add_u32 s26, s26, 0x1800
	s_addc_u32 s27, s27, 0
	global_load_dword v129, v115, s[26:27]
	s_add_u32 s26, s26, 0x1800
	s_addc_u32 s27, s27, 0
	global_load_dword v130, v115, s[26:27]
	s_add_u32 s26, s26, 0x1800
	s_addc_u32 s27, s27, 0
	global_load_dword v131, v115, s[26:27]
	s_add_u32 s26, s26, 0x1800
	s_addc_u32 s27, s27, 0
	global_load_dword v132, v115, s[26:27]
	s_add_u32 s26, s26, 0x1800
	s_addc_u32 s27, s27, 0
	global_load_dword v133, v115, s[26:27]
	s_add_u32 s26, s26, 0x1800
	s_addc_u32 s27, s27, 0
	global_load_dword v134, v115, s[26:27]
	s_add_u32 s26, s26, 0x1800
	s_addc_u32 s27, s27, 0
	global_load_dword v135, v115, s[26:27]
	s_add_u32 s26, s26, 0x1800
	s_addc_u32 s27, s27, 0
	global_load_dword v136, v115, s[26:27]
	s_add_u32 s26, s26, 0x1800
	s_addc_u32 s27, s27, 0
	global_load_dword v137, v115, s[26:27]
	s_add_u32 s26, s26, 0x1800
	s_addc_u32 s27, s27, 0
	global_load_dword v138, v115, s[26:27]
	s_add_u32 s26, s26, 0x1800
	s_addc_u32 s27, s27, 0
	global_load_dword v139, v115, s[26:27]
	s_add_u32 s26, s26, 0x1800
	s_addc_u32 s27, s27, 0
	global_load_dword v140, v115, s[26:27]
	s_add_u32 s26, s26, 0x1800
	s_addc_u32 s27, s27, 0
	global_load_dword v141, v115, s[26:27]
	s_add_u32 s26, s26, 0x1800
	s_addc_u32 s27, s27, 0
	global_load_dword v142, v115, s[26:27]
	s_add_u32 s26, s26, 0x1800
	s_addc_u32 s27, s27, 0
	global_load_dword v143, v115, s[26:27]
	s_add_u32 s26, s26, 0x1800
	s_addc_u32 s27, s27, 0
	global_load_dword v144, v115, s[26:27]
	s_add_u32 s26, s26, 0x1800
	s_addc_u32 s27, s27, 0
	global_load_dword v145, v115, s[26:27]
	s_add_u32 s26, s26, 0x1800
	s_addc_u32 s27, s27, 0
	global_load_dword v146, v115, s[26:27]
	s_add_u32 s26, s26, 0x1800
	s_addc_u32 s27, s27, 0
	global_load_dword v147, v115, s[26:27]
	s_add_u32 s26, s26, 0x1800
	s_addc_u32 s27, s27, 0
	global_load_dword v148, v115, s[26:27]
	s_add_u32 s26, s26, 0x1800
	s_addc_u32 s27, s27, 0
	global_load_dword v149, v115, s[26:27]
	s_add_u32 s26, s26, 0x1800
	s_addc_u32 s27, s27, 0
	global_load_dword v150, v115, s[26:27]
	s_add_u32 s26, s26, 0x1800
	s_addc_u32 s27, s27, 0
	global_load_dword v151, v115, s[26:27]
	s_add_u32 s26, s26, 0x1800
	s_addc_u32 s27, s27, 0
	global_load_dword v152, v115, s[26:27]
	s_add_u32 s26, s26, 0x1800
	s_addc_u32 s27, s27, 0
	global_load_dword v153, v115, s[26:27]
	s_add_u32 s26, s26, 0x1800
	s_addc_u32 s27, s27, 0
	global_load_dword v154, v115, s[26:27]
	s_add_u32 s26, s26, 0x1800
	s_addc_u32 s27, s27, 0
	global_load_dword v155, v115, s[26:27]
	s_add_u32 s26, s26, 0x1800
	s_addc_u32 s27, s27, 0
	global_load_dword v156, v115, s[26:27]
	s_add_u32 s26, s26, 0x1800
	s_addc_u32 s27, s27, 0
	global_load_dword v157, v115, s[26:27]
	s_add_u32 s26, s26, 0x1800
	s_addc_u32 s27, s27, 0
	global_load_dword v158, v115, s[26:27]
	s_add_u32 s26, s26, 0x1800
	s_addc_u32 s27, s27, 0
	global_load_dword v159, v115, s[26:27]
	s_waitcnt vmcnt(48)
; __device__ __forceinline__ void kraw_items(const Args& a, int gw, int NGW, int lane) {
;     ...
;             for (int ci = 0; ci < 12; ++ci) { const int c = c0 + 12 * cb + ci;
;                 float acc = 0.f;
; #pragma unroll
;                 for (int jj = 0; jj < 64; ++jj) acc += h[jj] * __builtin_bit_cast(float, __builtin_amdgcn_readlane(__builtin_bit_cast(int, wv[ci]), jj));
;                 const int cm = c % 768;
;                 const float delta = fabsf(-3.0701134573253945f + (float)cm * ((-15.350567286626973f + 3.0701134573253945f) / 767.0f));
;                 KR[(size_t)c * (LP + LS) + p] = acc * __expf(-tt * delta); }
	v_mfma_f32_32x32x2_f32 v[96:111], v64, v0, 0
	v_mfma_f32_32x32x2_f32 v[96:111], v65, v1, v[96:111]
	v_mfma_f32_32x32x2_f32 v[96:111], v66, v2, v[96:111]
	v_mfma_f32_32x32x2_f32 v[96:111], v67, v3, v[96:111]
	v_mfma_f32_32x32x2_f32 v[96:111], v68, v4, v[96:111]
	v_mfma_f32_32x32x2_f32 v[96:111], v69, v5, v[96:111]
	v_mfma_f32_32x32x2_f32 v[96:111], v70, v6, v[96:111]
	v_mfma_f32_32x32x2_f32 v[96:111], v71, v7, v[96:111]
	v_mfma_f32_32x32x2_f32 v[96:111], v72, v8, v[96:111]
	v_mfma_f32_32x32x2_f32 v[96:111], v73, v9, v[96:111]
	v_mfma_f32_32x32x2_f32 v[96:111], v74, v10, v[96:111]
	v_mfma_f32_32x32x2_f32 v[96:111], v75, v11, v[96:111]
	v_mfma_f32_32x32x2_f32 v[96:111], v76, v12, v[96:111]
	v_mfma_f32_32x32x2_f32 v[96:111], v77, v13, v[96:111]
	v_mfma_f32_32x32x2_f32 v[96:111], v78, v14, v[96:111]
	v_mfma_f32_32x32x2_f32 v[96:111], v79, v15, v[96:111]
	v_mfma_f32_32x32x2_f32 v[96:111], v80, v16, v[96:111]
	v_mfma_f32_32x32x2_f32 v[96:111], v81, v17, v[96:111]
	v_mfma_f32_32x32x2_f32 v[96:111], v82, v18, v[96:111]
	v_mfma_f32_32x32x2_f32 v[96:111], v83, v19, v[96:111]
	v_mfma_f32_32x32x2_f32 v[96:111], v84, v20, v[96:111]
	v_mfma_f32_32x32x2_f32 v[96:111], v85, v21, v[96:111]
	v_mfma_f32_32x32x2_f32 v[96:111], v86, v22, v[96:111]
	v_mfma_f32_32x32x2_f32 v[96:111], v87, v23, v[96:111]
	v_mfma_f32_32x32x2_f32 v[96:111], v88, v24, v[96:111]
	v_mfma_f32_32x32x2_f32 v[96:111], v89, v25, v[96:111]
	v_mfma_f32_32x32x2_f32 v[96:111], v90, v26, v[96:111]
	v_mfma_f32_32x32x2_f32 v[96:111], v91, v27, v[96:111]
	v_mfma_f32_32x32x2_f32 v[96:111], v92, v28, v[96:111]
	v_mfma_f32_32x32x2_f32 v[96:111], v93, v29, v[96:111]
	v_mfma_f32_32x32x2_f32 v[96:111], v94, v30, v[96:111]
	v_mfma_f32_32x32x2_f32 v[96:111], v95, v31, v[96:111]
	s_add_i32 s30, s29, 0
	v_add_u32_e32 v119, s30, v118
	v_cvt_f32_u32_e32 v119, v119
	v_fmamk_f32 v119, v119, 0xbc83298c, v120
	v_mul_f32_e64 v119, v117, |v119|
	v_mul_f32_e32 v119, 0x3fb8aa3b, v119
	v_exp_f32_e32 v160, v119
	s_add_i32 s30, s29, 1
	v_add_u32_e32 v119, s30, v118
	v_cvt_f32_u32_e32 v119, v119
	v_fmamk_f32 v119, v119, 0xbc83298c, v120
	v_mul_f32_e64 v119, v117, |v119|
	v_mul_f32_e32 v119, 0x3fb8aa3b, v119
	v_exp_f32_e32 v161, v119
	s_add_i32 s30, s29, 2
	v_add_u32_e32 v119, s30, v118
	v_cvt_f32_u32_e32 v119, v119
	v_fmamk_f32 v119, v119, 0xbc83298c, v120
	v_mul_f32_e64 v119, v117, |v119|
	v_mul_f32_e32 v119, 0x3fb8aa3b, v119
	v_exp_f32_e32 v162, v119
	s_add_i32 s30, s29, 3
	v_add_u32_e32 v119, s30, v118
	v_cvt_f32_u32_e32 v119, v119
	v_fmamk_f32 v119, v119, 0xbc83298c, v120
	v_mul_f32_e64 v119, v117, |v119|
	v_mul_f32_e32 v119, 0x3fb8aa3b, v119
	v_exp_f32_e32 v163, v119
	s_add_i32 s30, s29, 8
	v_add_u32_e32 v119, s30, v118
	v_cvt_f32_u32_e32 v119, v119
	v_fmamk_f32 v119, v119, 0xbc83298c, v120
	v_mul_f32_e64 v119, v117, |v119|
	v_mul_f32_e32 v119, 0x3fb8aa3b, v119
	v_exp_f32_e32 v164, v119
	s_add_i32 s30, s29, 9
	v_add_u32_e32 v119, s30, v118
	v_cvt_f32_u32_e32 v119, v119
	v_fmamk_f32 v119, v119, 0xbc83298c, v120
	v_mul_f32_e64 v119, v117, |v119|
	v_mul_f32_e32 v119, 0x3fb8aa3b, v119
	v_exp_f32_e32 v165, v119
	s_add_i32 s30, s29, 10
	v_add_u32_e32 v119, s30, v118
	v_cvt_f32_u32_e32 v119, v119
	v_fmamk_f32 v119, v119, 0xbc83298c, v120
	v_mul_f32_e64 v119, v117, |v119|
	v_mul_f32_e32 v119, 0x3fb8aa3b, v119
	v_exp_f32_e32 v166, v119
	s_add_i32 s30, s29, 11
	v_add_u32_e32 v119, s30, v118
	v_cvt_f32_u32_e32 v119, v119
	v_fmamk_f32 v119, v119, 0xbc83298c, v120
	v_mul_f32_e64 v119, v117, |v119|
	v_mul_f32_e32 v119, 0x3fb8aa3b, v119
	v_exp_f32_e32 v167, v119
	s_add_i32 s30, s29, 16
	v_add_u32_e32 v119, s30, v118
	v_cvt_f32_u32_e32 v119, v119
	v_fmamk_f32 v119, v119, 0xbc83298c, v120
	v_mul_f32_e64 v119, v117, |v119|
	v_mul_f32_e32 v119, 0x3fb8aa3b, v119
	v_exp_f32_e32 v168, v119
	s_add_i32 s30, s29, 17
	v_add_u32_e32 v119, s30, v118
	v_cvt_f32_u32_e32 v119, v119
	v_fmamk_f32 v119, v119, 0xbc83298c, v120
	v_mul_f32_e64 v119, v117, |v119|
	v_mul_f32_e32 v119, 0x3fb8aa3b, v119
	v_exp_f32_e32 v169, v119
	s_add_i32 s30, s29, 18
	v_add_u32_e32 v119, s30, v118
	v_cvt_f32_u32_e32 v119, v119
	v_fmamk_f32 v119, v119, 0xbc83298c, v120
	v_mul_f32_e64 v119, v117, |v119|
	v_mul_f32_e32 v119, 0x3fb8aa3b, v119
	v_exp_f32_e32 v170, v119
	s_add_i32 s30, s29, 19
	v_add_u32_e32 v119, s30, v118
	v_cvt_f32_u32_e32 v119, v119
	v_fmamk_f32 v119, v119, 0xbc83298c, v120
	v_mul_f32_e64 v119, v117, |v119|
	v_mul_f32_e32 v119, 0x3fb8aa3b, v119
	v_exp_f32_e32 v171, v119
	s_add_i32 s30, s29, 24
	v_add_u32_e32 v119, s30, v118
	v_cvt_f32_u32_e32 v119, v119
	v_fmamk_f32 v119, v119, 0xbc83298c, v120
	v_mul_f32_e64 v119, v117, |v119|
	v_mul_f32_e32 v119, 0x3fb8aa3b, v119
	v_exp_f32_e32 v172, v119
	s_add_i32 s30, s29, 25
	v_add_u32_e32 v119, s30, v118
	v_cvt_f32_u32_e32 v119, v119
	v_fmamk_f32 v119, v119, 0xbc83298c, v120
	v_mul_f32_e64 v119, v117, |v119|
	v_mul_f32_e32 v119, 0x3fb8aa3b, v119
	v_exp_f32_e32 v173, v119
	s_add_i32 s30, s29, 26
	v_add_u32_e32 v119, s30, v118
	v_cvt_f32_u32_e32 v119, v119
	v_fmamk_f32 v119, v119, 0xbc83298c, v120
	v_mul_f32_e64 v119, v117, |v119|
	v_mul_f32_e32 v119, 0x3fb8aa3b, v119
	v_exp_f32_e32 v174, v119
	s_add_i32 s30, s29, 27
	v_add_u32_e32 v119, s30, v118
	v_cvt_f32_u32_e32 v119, v119
	v_fmamk_f32 v119, v119, 0xbc83298c, v120
	v_mul_f32_e64 v119, v117, |v119|
	v_mul_f32_e32 v119, 0x3fb8aa3b, v119
	v_exp_f32_e32 v175, v119
	s_nop 7
	v_mul_f32_e32 v176, v96, v160
	s_mov_b64 s[36:37], s[34:35]
	global_store_dword v115, v176, s[36:37]
	v_mul_f32_e32 v177, v97, v161
	s_add_u32 s36, s34, 0xc000
	s_addc_u32 s37, s35, 0
	global_store_dword v115, v177, s[36:37]
	v_mul_f32_e32 v178, v98, v162
	s_add_u32 s36, s34, 0x18000
; __device__ __forceinline__ void kraw_items(const Args& a, int gw, int NGW, int lane) {
;     ...
;             const float* wr = a.in[I_FWOUT] + lane * 1536 + c0 + 12 * cb;
;             const f32x4 w0 = *(const f32x4*)(wr), w1 = *(const f32x4*)(wr + 4), w2 = *(const f32x4*)(wr + 8);
;             float wv[12] = {w0.x, w0.y, w0.z, w0.w, w1.x, w1.y, w1.z, w1.w, w2.x, w2.y, w2.z, w2.w};
; #pragma unroll
;             for (int ci = 0; ci < 12; ++ci) { const int c = c0 + 12 * cb + ci;
;                 float acc = 0.f;
; #pragma unroll
;                 for (int jj = 0; jj < 64; ++jj) acc += h[jj] * __builtin_bit_cast(float, __builtin_amdgcn_readlane(__builtin_bit_cast(int, wv[ci]), jj));
;                 const int cm = c % 768;
;                 const float delta = fabsf(-3.0701134573253945f + (float)cm * ((-15.350567286626973f + 3.0701134573253945f) / 767.0f));
;                 KR[(size_t)c * (LP + LS) + p] = acc * __expf(-tt * delta); }
	s_addc_u32 s37, s35, 0
	global_store_dword v115, v178, s[36:37]
	v_mul_f32_e32 v179, v99, v163
	s_add_u32 s36, s34, 0x24000
	s_addc_u32 s37, s35, 0
	global_store_dword v115, v179, s[36:37]
	v_mul_f32_e32 v180, v100, v164
	s_add_u32 s36, s34, 0x60000
	s_addc_u32 s37, s35, 0
	global_store_dword v115, v180, s[36:37]
	v_mul_f32_e32 v181, v101, v165
	s_add_u32 s36, s34, 0x6c000
	s_addc_u32 s37, s35, 0
	global_store_dword v115, v181, s[36:37]
	v_mul_f32_e32 v182, v102, v166
	s_add_u32 s36, s34, 0x78000
	s_addc_u32 s37, s35, 0
	global_store_dword v115, v182, s[36:37]
	v_mul_f32_e32 v183, v103, v167
	s_add_u32 s36, s34, 0x84000
	s_addc_u32 s37, s35, 0
	global_store_dword v115, v183, s[36:37]
	v_mul_f32_e32 v184, v104, v168
	s_add_u32 s36, s34, 0xc0000
	s_addc_u32 s37, s35, 0
	global_store_dword v115, v184, s[36:37]
	v_mul_f32_e32 v185, v105, v169
	s_add_u32 s36, s34, 0xcc000
	s_addc_u32 s37, s35, 0
	global_store_dword v115, v185, s[36:37]
	v_mul_f32_e32 v186, v106, v170
	s_add_u32 s36, s34, 0xd8000
	s_addc_u32 s37, s35, 0
	global_store_dword v115, v186, s[36:37]
	v_mul_f32_e32 v187, v107, v171
	s_add_u32 s36, s34, 0xe4000
	s_addc_u32 s37, s35, 0
	global_store_dword v115, v187, s[36:37]
	v_mul_f32_e32 v188, v108, v172
	s_add_u32 s36, s34, 0x120000
	s_addc_u32 s37, s35, 0
	global_store_dword v115, v188, s[36:37]
	v_mul_f32_e32 v189, v109, v173
	s_add_u32 s36, s34, 0x12c000
	s_addc_u32 s37, s35, 0
	global_store_dword v115, v189, s[36:37]
	v_mul_f32_e32 v190, v110, v174
	s_add_u32 s36, s34, 0x138000
	s_addc_u32 s37, s35, 0
	global_store_dword v115, v190, s[36:37]
	v_mul_f32_e32 v191, v111, v175
	s_add_u32 s36, s34, 0x144000
	s_addc_u32 s37, s35, 0
	global_store_dword v115, v191, s[36:37]
	s_add_i32 s28, s21, 32
	s_sub_i32 s29, s28, 0x300
	s_cmp_ge_u32 s28, 0x300
	s_cselect_b32 s29, s29, s28
	s_mul_i32 s30, s28, 0xc000
	s_lshl_b32 s35, s20, 2
	s_add_u32 s30, s30, s35
	s_add_u32 s34, s14, s30
	s_addc_u32 s35, s15, 0
	s_add_i32 s30, s21, 64
	s_lshl_b32 s30, s30, 2
	s_add_u32 s26, s6, s30
	s_addc_u32 s27, s7, 0
	global_load_dword v64, v115, s[26:27]
	s_add_u32 s26, s26, 0x1800
	s_addc_u32 s27, s27, 0
	global_load_dword v65, v115, s[26:27]
	s_add_u32 s26, s26, 0x1800
	s_addc_u32 s27, s27, 0
	global_load_dword v66, v115, s[26:27]
	s_add_u32 s26, s26, 0x1800
	s_addc_u32 s27, s27, 0
	global_load_dword v67, v115, s[26:27]
	s_add_u32 s26, s26, 0x1800
	s_addc_u32 s27, s27, 0
	global_load_dword v68, v115, s[26:27]
	s_add_u32 s26, s26, 0x1800
	s_addc_u32 s27, s27, 0
	global_load_dword v69, v115, s[26:27]
	s_add_u32 s26, s26, 0x1800
	s_addc_u32 s27, s27, 0
	global_load_dword v70, v115, s[26:27]
	s_add_u32 s26, s26, 0x1800
	s_addc_u32 s27, s27, 0
	global_load_dword v71, v115, s[26:27]
	s_add_u32 s26, s26, 0x1800
	s_addc_u32 s27, s27, 0
	global_load_dword v72, v115, s[26:27]
	s_add_u32 s26, s26, 0x1800
	s_addc_u32 s27, s27, 0
	global_load_dword v73, v115, s[26:27]
	s_add_u32 s26, s26, 0x1800
	s_addc_u32 s27, s27, 0
	global_load_dword v74, v115, s[26:27]
	s_add_u32 s26, s26, 0x1800
	s_addc_u32 s27, s27, 0
	global_load_dword v75, v115, s[26:27]
	s_add_u32 s26, s26, 0x1800
	s_addc_u32 s27, s27, 0
	global_load_dword v76, v115, s[26:27]
	s_add_u32 s26, s26, 0x1800
	s_addc_u32 s27, s27, 0
	global_load_dword v77, v115, s[26:27]
	s_add_u32 s26, s26, 0x1800
	s_addc_u32 s27, s27, 0
	global_load_dword v78, v115, s[26:27]
	s_add_u32 s26, s26, 0x1800
	s_addc_u32 s27, s27, 0
	global_load_dword v79, v115, s[26:27]
	s_add_u32 s26, s26, 0x1800
	s_addc_u32 s27, s27, 0
	global_load_dword v80, v115, s[26:27]
	s_add_u32 s26, s26, 0x1800
	s_addc_u32 s27, s27, 0
	global_load_dword v81, v115, s[26:27]
	s_add_u32 s26, s26, 0x1800
	s_addc_u32 s27, s27, 0
	global_load_dword v82, v115, s[26:27]
	s_add_u32 s26, s26, 0x1800
	s_addc_u32 s27, s27, 0
	global_load_dword v83, v115, s[26:27]
	s_add_u32 s26, s26, 0x1800
	s_addc_u32 s27, s27, 0
	global_load_dword v84, v115, s[26:27]
	s_add_u32 s26, s26, 0x1800
	s_addc_u32 s27, s27, 0
	global_load_dword v85, v115, s[26:27]
	s_add_u32 s26, s26, 0x1800
	s_addc_u32 s27, s27, 0
	global_load_dword v86, v115, s[26:27]
	s_add_u32 s26, s26, 0x1800
	s_addc_u32 s27, s27, 0
	global_load_dword v87, v115, s[26:27]
	s_add_u32 s26, s26, 0x1800
	s_addc_u32 s27, s27, 0
	global_load_dword v88, v115, s[26:27]
	s_add_u32 s26, s26, 0x1800
	s_addc_u32 s27, s27, 0
	global_load_dword v89, v115, s[26:27]
	s_add_u32 s26, s26, 0x1800
	s_addc_u32 s27, s27, 0
	global_load_dword v90, v115, s[26:27]
	s_add_u32 s26, s26, 0x1800
	s_addc_u32 s27, s27, 0
	global_load_dword v91, v115, s[26:27]
	s_add_u32 s26, s26, 0x1800
	s_addc_u32 s27, s27, 0
	global_load_dword v92, v115, s[26:27]
	s_add_u32 s26, s26, 0x1800
	s_addc_u32 s27, s27, 0
	global_load_dword v93, v115, s[26:27]
	s_add_u32 s26, s26, 0x1800
	s_addc_u32 s27, s27, 0
	global_load_dword v94, v115, s[26:27]
	s_add_u32 s26, s26, 0x1800
	s_addc_u32 s27, s27, 0
	global_load_dword v95, v115, s[26:27]
	s_waitcnt vmcnt(48)
; __device__ __forceinline__ void kraw_items(const Args& a, int gw, int NGW, int lane) {
;     ...
;             for (int ci = 0; ci < 12; ++ci) { const int c = c0 + 12 * cb + ci;
;                 float acc = 0.f;
; #pragma unroll
;                 for (int jj = 0; jj < 64; ++jj) acc += h[jj] * __builtin_bit_cast(float, __builtin_amdgcn_readlane(__builtin_bit_cast(int, wv[ci]), jj));
;                 const int cm = c % 768;
;                 const float delta = fabsf(-3.0701134573253945f + (float)cm * ((-15.350567286626973f + 3.0701134573253945f) / 767.0f));
;                 KR[(size_t)c * (LP + LS) + p] = acc * __expf(-tt * delta); }
	v_mfma_f32_32x32x2_f32 v[96:111], v128, v0, 0
	v_mfma_f32_32x32x2_f32 v[96:111], v129, v1, v[96:111]
	v_mfma_f32_32x32x2_f32 v[96:111], v130, v2, v[96:111]
	v_mfma_f32_32x32x2_f32 v[96:111], v131, v3, v[96:111]
	v_mfma_f32_32x32x2_f32 v[96:111], v132, v4, v[96:111]
	v_mfma_f32_32x32x2_f32 v[96:111], v133, v5, v[96:111]
	v_mfma_f32_32x32x2_f32 v[96:111], v134, v6, v[96:111]
	v_mfma_f32_32x32x2_f32 v[96:111], v135, v7, v[96:111]
	v_mfma_f32_32x32x2_f32 v[96:111], v136, v8, v[96:111]
	v_mfma_f32_32x32x2_f32 v[96:111], v137, v9, v[96:111]
	v_mfma_f32_32x32x2_f32 v[96:111], v138, v10, v[96:111]
	v_mfma_f32_32x32x2_f32 v[96:111], v139, v11, v[96:111]
	v_mfma_f32_32x32x2_f32 v[96:111], v140, v12, v[96:111]
	v_mfma_f32_32x32x2_f32 v[96:111], v141, v13, v[96:111]
	v_mfma_f32_32x32x2_f32 v[96:111], v142, v14, v[96:111]
	v_mfma_f32_32x32x2_f32 v[96:111], v143, v15, v[96:111]
	v_mfma_f32_32x32x2_f32 v[96:111], v144, v16, v[96:111]
	v_mfma_f32_32x32x2_f32 v[96:111], v145, v17, v[96:111]
	v_mfma_f32_32x32x2_f32 v[96:111], v146, v18, v[96:111]
	v_mfma_f32_32x32x2_f32 v[96:111], v147, v19, v[96:111]
	v_mfma_f32_32x32x2_f32 v[96:111], v148, v20, v[96:111]
	v_mfma_f32_32x32x2_f32 v[96:111], v149, v21, v[96:111]
	v_mfma_f32_32x32x2_f32 v[96:111], v150, v22, v[96:111]
	v_mfma_f32_32x32x2_f32 v[96:111], v151, v23, v[96:111]
	v_mfma_f32_32x32x2_f32 v[96:111], v152, v24, v[96:111]
	v_mfma_f32_32x32x2_f32 v[96:111], v153, v25, v[96:111]
	v_mfma_f32_32x32x2_f32 v[96:111], v154, v26, v[96:111]
	v_mfma_f32_32x32x2_f32 v[96:111], v155, v27, v[96:111]
	v_mfma_f32_32x32x2_f32 v[96:111], v156, v28, v[96:111]
	v_mfma_f32_32x32x2_f32 v[96:111], v157, v29, v[96:111]
	v_mfma_f32_32x32x2_f32 v[96:111], v158, v30, v[96:111]
	v_mfma_f32_32x32x2_f32 v[96:111], v159, v31, v[96:111]
	s_add_i32 s30, s29, 0
	v_add_u32_e32 v119, s30, v118
	v_cvt_f32_u32_e32 v119, v119
	v_fmamk_f32 v119, v119, 0xbc83298c, v120
	v_mul_f32_e64 v119, v117, |v119|
	v_mul_f32_e32 v119, 0x3fb8aa3b, v119
	v_exp_f32_e32 v160, v119
	s_add_i32 s30, s29, 1
	v_add_u32_e32 v119, s30, v118
	v_cvt_f32_u32_e32 v119, v119
	v_fmamk_f32 v119, v119, 0xbc83298c, v120
	v_mul_f32_e64 v119, v117, |v119|
	v_mul_f32_e32 v119, 0x3fb8aa3b, v119
	v_exp_f32_e32 v161, v119
	s_add_i32 s30, s29, 2
	v_add_u32_e32 v119, s30, v118
	v_cvt_f32_u32_e32 v119, v119
	v_fmamk_f32 v119, v119, 0xbc83298c, v120
	v_mul_f32_e64 v119, v117, |v119|
	v_mul_f32_e32 v119, 0x3fb8aa3b, v119
	v_exp_f32_e32 v162, v119
	s_add_i32 s30, s29, 3
	v_add_u32_e32 v119, s30, v118
	v_cvt_f32_u32_e32 v119, v119
	v_fmamk_f32 v119, v119, 0xbc83298c, v120
	v_mul_f32_e64 v119, v117, |v119|
	v_mul_f32_e32 v119, 0x3fb8aa3b, v119
	v_exp_f32_e32 v163, v119
	s_add_i32 s30, s29, 8
	v_add_u32_e32 v119, s30, v118
	v_cvt_f32_u32_e32 v119, v119
	v_fmamk_f32 v119, v119, 0xbc83298c, v120
	v_mul_f32_e64 v119, v117, |v119|
	v_mul_f32_e32 v119, 0x3fb8aa3b, v119
	v_exp_f32_e32 v164, v119
	s_add_i32 s30, s29, 9
	v_add_u32_e32 v119, s30, v118
	v_cvt_f32_u32_e32 v119, v119
	v_fmamk_f32 v119, v119, 0xbc83298c, v120
	v_mul_f32_e64 v119, v117, |v119|
	v_mul_f32_e32 v119, 0x3fb8aa3b, v119
	v_exp_f32_e32 v165, v119
	s_add_i32 s30, s29, 10
	v_add_u32_e32 v119, s30, v118
	v_cvt_f32_u32_e32 v119, v119
	v_fmamk_f32 v119, v119, 0xbc83298c, v120
	v_mul_f32_e64 v119, v117, |v119|
	v_mul_f32_e32 v119, 0x3fb8aa3b, v119
	v_exp_f32_e32 v166, v119
	s_add_i32 s30, s29, 11
	v_add_u32_e32 v119, s30, v118
	v_cvt_f32_u32_e32 v119, v119
	v_fmamk_f32 v119, v119, 0xbc83298c, v120
	v_mul_f32_e64 v119, v117, |v119|
	v_mul_f32_e32 v119, 0x3fb8aa3b, v119
	v_exp_f32_e32 v167, v119
	s_add_i32 s30, s29, 16
	v_add_u32_e32 v119, s30, v118
	v_cvt_f32_u32_e32 v119, v119
	v_fmamk_f32 v119, v119, 0xbc83298c, v120
	v_mul_f32_e64 v119, v117, |v119|
	v_mul_f32_e32 v119, 0x3fb8aa3b, v119
	v_exp_f32_e32 v168, v119
	s_add_i32 s30, s29, 17
	v_add_u32_e32 v119, s30, v118
	v_cvt_f32_u32_e32 v119, v119
	v_fmamk_f32 v119, v119, 0xbc83298c, v120
	v_mul_f32_e64 v119, v117, |v119|
	v_mul_f32_e32 v119, 0x3fb8aa3b, v119
	v_exp_f32_e32 v169, v119
	s_add_i32 s30, s29, 18
	v_add_u32_e32 v119, s30, v118
	v_cvt_f32_u32_e32 v119, v119
	v_fmamk_f32 v119, v119, 0xbc83298c, v120
	v_mul_f32_e64 v119, v117, |v119|
	v_mul_f32_e32 v119, 0x3fb8aa3b, v119
	v_exp_f32_e32 v170, v119
	s_add_i32 s30, s29, 19
	v_add_u32_e32 v119, s30, v118
	v_cvt_f32_u32_e32 v119, v119
	v_fmamk_f32 v119, v119, 0xbc83298c, v120
	v_mul_f32_e64 v119, v117, |v119|
	v_mul_f32_e32 v119, 0x3fb8aa3b, v119
	v_exp_f32_e32 v171, v119
	s_add_i32 s30, s29, 24
	v_add_u32_e32 v119, s30, v118
	v_cvt_f32_u32_e32 v119, v119
	v_fmamk_f32 v119, v119, 0xbc83298c, v120
	v_mul_f32_e64 v119, v117, |v119|
	v_mul_f32_e32 v119, 0x3fb8aa3b, v119
	v_exp_f32_e32 v172, v119
	s_add_i32 s30, s29, 25
	v_add_u32_e32 v119, s30, v118
	v_cvt_f32_u32_e32 v119, v119
	v_fmamk_f32 v119, v119, 0xbc83298c, v120
	v_mul_f32_e64 v119, v117, |v119|
	v_mul_f32_e32 v119, 0x3fb8aa3b, v119
	v_exp_f32_e32 v173, v119
	s_add_i32 s30, s29, 26
	v_add_u32_e32 v119, s30, v118
	v_cvt_f32_u32_e32 v119, v119
	v_fmamk_f32 v119, v119, 0xbc83298c, v120
	v_mul_f32_e64 v119, v117, |v119|
	v_mul_f32_e32 v119, 0x3fb8aa3b, v119
	v_exp_f32_e32 v174, v119
	s_add_i32 s30, s29, 27
	v_add_u32_e32 v119, s30, v118
	v_cvt_f32_u32_e32 v119, v119
	v_fmamk_f32 v119, v119, 0xbc83298c, v120
	v_mul_f32_e64 v119, v117, |v119|
	v_mul_f32_e32 v119, 0x3fb8aa3b, v119
	v_exp_f32_e32 v175, v119
	s_nop 7
	v_mul_f32_e32 v176, v96, v160
	s_mov_b64 s[36:37], s[34:35]
	global_store_dword v115, v176, s[36:37]
	v_mul_f32_e32 v177, v97, v161
	s_add_u32 s36, s34, 0xc000
	s_addc_u32 s37, s35, 0
	global_store_dword v115, v177, s[36:37]
	v_mul_f32_e32 v178, v98, v162
; __device__ __forceinline__ void kraw_items(const Args& a, int gw, int NGW, int lane) {
;     ...
;             const float* wr = a.in[I_FWOUT] + lane * 1536 + c0 + 12 * cb;
;             const f32x4 w0 = *(const f32x4*)(wr), w1 = *(const f32x4*)(wr + 4), w2 = *(const f32x4*)(wr + 8);
;             float wv[12] = {w0.x, w0.y, w0.z, w0.w, w1.x, w1.y, w1.z, w1.w, w2.x, w2.y, w2.z, w2.w};
; #pragma unroll
;             for (int ci = 0; ci < 12; ++ci) { const int c = c0 + 12 * cb + ci;
;                 float acc = 0.f;
; #pragma unroll
;                 for (int jj = 0; jj < 64; ++jj) acc += h[jj] * __builtin_bit_cast(float, __builtin_amdgcn_readlane(__builtin_bit_cast(int, wv[ci]), jj));
;                 const int cm = c % 768;
;                 const float delta = fabsf(-3.0701134573253945f + (float)cm * ((-15.350567286626973f + 3.0701134573253945f) / 767.0f));
;                 KR[(size_t)c * (LP + LS) + p] = acc * __expf(-tt * delta); }
	s_add_u32 s36, s34, 0x18000
	s_addc_u32 s37, s35, 0
	global_store_dword v115, v178, s[36:37]
	v_mul_f32_e32 v179, v99, v163
	s_add_u32 s36, s34, 0x24000
	s_addc_u32 s37, s35, 0
	global_store_dword v115, v179, s[36:37]
	v_mul_f32_e32 v180, v100, v164
	s_add_u32 s36, s34, 0x60000
	s_addc_u32 s37, s35, 0
	global_store_dword v115, v180, s[36:37]
	v_mul_f32_e32 v181, v101, v165
	s_add_u32 s36, s34, 0x6c000
	s_addc_u32 s37, s35, 0
	global_store_dword v115, v181, s[36:37]
	v_mul_f32_e32 v182, v102, v166
	s_add_u32 s36, s34, 0x78000
	s_addc_u32 s37, s35, 0
	global_store_dword v115, v182, s[36:37]
	v_mul_f32_e32 v183, v103, v167
	s_add_u32 s36, s34, 0x84000
	s_addc_u32 s37, s35, 0
	global_store_dword v115, v183, s[36:37]
	v_mul_f32_e32 v184, v104, v168
	s_add_u32 s36, s34, 0xc0000
	s_addc_u32 s37, s35, 0
	global_store_dword v115, v184, s[36:37]
	v_mul_f32_e32 v185, v105, v169
	s_add_u32 s36, s34, 0xcc000
	s_addc_u32 s37, s35, 0
	global_store_dword v115, v185, s[36:37]
	v_mul_f32_e32 v186, v106, v170
	s_add_u32 s36, s34, 0xd8000
	s_addc_u32 s37, s35, 0
	global_store_dword v115, v186, s[36:37]
	v_mul_f32_e32 v187, v107, v171
	s_add_u32 s36, s34, 0xe4000
	s_addc_u32 s37, s35, 0
	global_store_dword v115, v187, s[36:37]
	v_mul_f32_e32 v188, v108, v172
	s_add_u32 s36, s34, 0x120000
	s_addc_u32 s37, s35, 0
	global_store_dword v115, v188, s[36:37]
	v_mul_f32_e32 v189, v109, v173
	s_add_u32 s36, s34, 0x12c000
	s_addc_u32 s37, s35, 0
	global_store_dword v115, v189, s[36:37]
	v_mul_f32_e32 v190, v110, v174
	s_add_u32 s36, s34, 0x138000
	s_addc_u32 s37, s35, 0
	global_store_dword v115, v190, s[36:37]
	v_mul_f32_e32 v191, v111, v175
	s_add_u32 s36, s34, 0x144000
	s_addc_u32 s37, s35, 0
	global_store_dword v115, v191, s[36:37]
	s_add_i32 s28, s21, 64
	s_sub_i32 s29, s28, 0x300
	s_cmp_ge_u32 s28, 0x300
	s_cselect_b32 s29, s29, s28
	s_mul_i32 s30, s28, 0xc000
	s_lshl_b32 s35, s20, 2
	s_add_u32 s30, s30, s35
	s_add_u32 s34, s14, s30
	s_addc_u32 s35, s15, 0
	s_waitcnt vmcnt(16)
	v_mfma_f32_32x32x2_f32 v[96:111], v64, v0, 0
	v_mfma_f32_32x32x2_f32 v[96:111], v65, v1, v[96:111]
	v_mfma_f32_32x32x2_f32 v[96:111], v66, v2, v[96:111]
	v_mfma_f32_32x32x2_f32 v[96:111], v67, v3, v[96:111]
	v_mfma_f32_32x32x2_f32 v[96:111], v68, v4, v[96:111]
	v_mfma_f32_32x32x2_f32 v[96:111], v69, v5, v[96:111]
	v_mfma_f32_32x32x2_f32 v[96:111], v70, v6, v[96:111]
	v_mfma_f32_32x32x2_f32 v[96:111], v71, v7, v[96:111]
	v_mfma_f32_32x32x2_f32 v[96:111], v72, v8, v[96:111]
	v_mfma_f32_32x32x2_f32 v[96:111], v73, v9, v[96:111]
	v_mfma_f32_32x32x2_f32 v[96:111], v74, v10, v[96:111]
	v_mfma_f32_32x32x2_f32 v[96:111], v75, v11, v[96:111]
	v_mfma_f32_32x32x2_f32 v[96:111], v76, v12, v[96:111]
	v_mfma_f32_32x32x2_f32 v[96:111], v77, v13, v[96:111]
	v_mfma_f32_32x32x2_f32 v[96:111], v78, v14, v[96:111]
	v_mfma_f32_32x32x2_f32 v[96:111], v79, v15, v[96:111]
	v_mfma_f32_32x32x2_f32 v[96:111], v80, v16, v[96:111]
	v_mfma_f32_32x32x2_f32 v[96:111], v81, v17, v[96:111]
	v_mfma_f32_32x32x2_f32 v[96:111], v82, v18, v[96:111]
	v_mfma_f32_32x32x2_f32 v[96:111], v83, v19, v[96:111]
	v_mfma_f32_32x32x2_f32 v[96:111], v84, v20, v[96:111]
	v_mfma_f32_32x32x2_f32 v[96:111], v85, v21, v[96:111]
	v_mfma_f32_32x32x2_f32 v[96:111], v86, v22, v[96:111]
	v_mfma_f32_32x32x2_f32 v[96:111], v87, v23, v[96:111]
	v_mfma_f32_32x32x2_f32 v[96:111], v88, v24, v[96:111]
	v_mfma_f32_32x32x2_f32 v[96:111], v89, v25, v[96:111]
	v_mfma_f32_32x32x2_f32 v[96:111], v90, v26, v[96:111]
	v_mfma_f32_32x32x2_f32 v[96:111], v91, v27, v[96:111]
	v_mfma_f32_32x32x2_f32 v[96:111], v92, v28, v[96:111]
	v_mfma_f32_32x32x2_f32 v[96:111], v93, v29, v[96:111]
	v_mfma_f32_32x32x2_f32 v[96:111], v94, v30, v[96:111]
	v_mfma_f32_32x32x2_f32 v[96:111], v95, v31, v[96:111]
	s_add_i32 s30, s29, 0
	v_add_u32_e32 v119, s30, v118
	v_cvt_f32_u32_e32 v119, v119
	v_fmamk_f32 v119, v119, 0xbc83298c, v120
	v_mul_f32_e64 v119, v117, |v119|
	v_mul_f32_e32 v119, 0x3fb8aa3b, v119
	v_exp_f32_e32 v160, v119
	s_add_i32 s30, s29, 1
	v_add_u32_e32 v119, s30, v118
	v_cvt_f32_u32_e32 v119, v119
	v_fmamk_f32 v119, v119, 0xbc83298c, v120
	v_mul_f32_e64 v119, v117, |v119|
	v_mul_f32_e32 v119, 0x3fb8aa3b, v119
	v_exp_f32_e32 v161, v119
	s_add_i32 s30, s29, 2
	v_add_u32_e32 v119, s30, v118
	v_cvt_f32_u32_e32 v119, v119
	v_fmamk_f32 v119, v119, 0xbc83298c, v120
	v_mul_f32_e64 v119, v117, |v119|
	v_mul_f32_e32 v119, 0x3fb8aa3b, v119
	v_exp_f32_e32 v162, v119
	s_add_i32 s30, s29, 3
	v_add_u32_e32 v119, s30, v118
	v_cvt_f32_u32_e32 v119, v119
	v_fmamk_f32 v119, v119, 0xbc83298c, v120
	v_mul_f32_e64 v119, v117, |v119|
	v_mul_f32_e32 v119, 0x3fb8aa3b, v119
	v_exp_f32_e32 v163, v119
	s_add_i32 s30, s29, 8
; __device__ __forceinline__ void kraw_items(const Args& a, int gw, int NGW, int lane) {
;     ...
;                 const int cm = c % 768;
;                 const float delta = fabsf(-3.0701134573253945f + (float)cm * ((-15.350567286626973f + 3.0701134573253945f) / 767.0f));
;                 KR[(size_t)c * (LP + LS) + p] = acc * __expf(-tt * delta); }
	v_add_u32_e32 v119, s30, v118
	v_cvt_f32_u32_e32 v119, v119
	v_fmamk_f32 v119, v119, 0xbc83298c, v120
	v_mul_f32_e64 v119, v117, |v119|
	v_mul_f32_e32 v119, 0x3fb8aa3b, v119
	v_exp_f32_e32 v164, v119
	s_add_i32 s30, s29, 9
	v_add_u32_e32 v119, s30, v118
	v_cvt_f32_u32_e32 v119, v119
	v_fmamk_f32 v119, v119, 0xbc83298c, v120
	v_mul_f32_e64 v119, v117, |v119|
	v_mul_f32_e32 v119, 0x3fb8aa3b, v119
	v_exp_f32_e32 v165, v119
	s_add_i32 s30, s29, 10
	v_add_u32_e32 v119, s30, v118
	v_cvt_f32_u32_e32 v119, v119
	v_fmamk_f32 v119, v119, 0xbc83298c, v120
	v_mul_f32_e64 v119, v117, |v119|
	v_mul_f32_e32 v119, 0x3fb8aa3b, v119
	v_exp_f32_e32 v166, v119
	s_add_i32 s30, s29, 11
	v_add_u32_e32 v119, s30, v118
	v_cvt_f32_u32_e32 v119, v119
	v_fmamk_f32 v119, v119, 0xbc83298c, v120
	v_mul_f32_e64 v119, v117, |v119|
	v_mul_f32_e32 v119, 0x3fb8aa3b, v119
	v_exp_f32_e32 v167, v119
	s_add_i32 s30, s29, 16
	v_add_u32_e32 v119, s30, v118
	v_cvt_f32_u32_e32 v119, v119
	v_fmamk_f32 v119, v119, 0xbc83298c, v120
	v_mul_f32_e64 v119, v117, |v119|
	v_mul_f32_e32 v119, 0x3fb8aa3b, v119
	v_exp_f32_e32 v168, v119
	s_add_i32 s30, s29, 17
	v_add_u32_e32 v119, s30, v118
	v_cvt_f32_u32_e32 v119, v119
	v_fmamk_f32 v119, v119, 0xbc83298c, v120
	v_mul_f32_e64 v119, v117, |v119|
	v_mul_f32_e32 v119, 0x3fb8aa3b, v119
	v_exp_f32_e32 v169, v119
	s_add_i32 s30, s29, 18
	v_add_u32_e32 v119, s30, v118
	v_cvt_f32_u32_e32 v119, v119
	v_fmamk_f32 v119, v119, 0xbc83298c, v120
	v_mul_f32_e64 v119, v117, |v119|
	v_mul_f32_e32 v119, 0x3fb8aa3b, v119
	v_exp_f32_e32 v170, v119
	s_add_i32 s30, s29, 19
	v_add_u32_e32 v119, s30, v118
	v_cvt_f32_u32_e32 v119, v119
	v_fmamk_f32 v119, v119, 0xbc83298c, v120
	v_mul_f32_e64 v119, v117, |v119|
	v_mul_f32_e32 v119, 0x3fb8aa3b, v119
	v_exp_f32_e32 v171, v119
	s_add_i32 s30, s29, 24
	v_add_u32_e32 v119, s30, v118
	v_cvt_f32_u32_e32 v119, v119
	v_fmamk_f32 v119, v119, 0xbc83298c, v120
	v_mul_f32_e64 v119, v117, |v119|
	v_mul_f32_e32 v119, 0x3fb8aa3b, v119
	v_exp_f32_e32 v172, v119
	s_add_i32 s30, s29, 25
	v_add_u32_e32 v119, s30, v118
	v_cvt_f32_u32_e32 v119, v119
	v_fmamk_f32 v119, v119, 0xbc83298c, v120
	v_mul_f32_e64 v119, v117, |v119|
	v_mul_f32_e32 v119, 0x3fb8aa3b, v119
	v_exp_f32_e32 v173, v119
	s_add_i32 s30, s29, 26
	v_add_u32_e32 v119, s30, v118
	v_cvt_f32_u32_e32 v119, v119
	v_fmamk_f32 v119, v119, 0xbc83298c, v120
	v_mul_f32_e64 v119, v117, |v119|
	v_mul_f32_e32 v119, 0x3fb8aa3b, v119
	v_exp_f32_e32 v174, v119
	s_add_i32 s30, s29, 27
	v_add_u32_e32 v119, s30, v118
	v_cvt_f32_u32_e32 v119, v119
	v_fmamk_f32 v119, v119, 0xbc83298c, v120
	v_mul_f32_e64 v119, v117, |v119|
	v_mul_f32_e32 v119, 0x3fb8aa3b, v119
	v_exp_f32_e32 v175, v119
	s_nop 7
	v_mul_f32_e32 v176, v96, v160
	s_mov_b64 s[36:37], s[34:35]
	global_store_dword v115, v176, s[36:37]
	v_mul_f32_e32 v177, v97, v161
	s_add_u32 s36, s34, 0xc000
	s_addc_u32 s37, s35, 0
	global_store_dword v115, v177, s[36:37]
	v_mul_f32_e32 v178, v98, v162
	s_add_u32 s36, s34, 0x18000
	s_addc_u32 s37, s35, 0
	global_store_dword v115, v178, s[36:37]
	v_mul_f32_e32 v179, v99, v163
	s_add_u32 s36, s34, 0x24000
	s_addc_u32 s37, s35, 0
	global_store_dword v115, v179, s[36:37]
	v_mul_f32_e32 v180, v100, v164
	s_add_u32 s36, s34, 0x60000
	s_addc_u32 s37, s35, 0
	global_store_dword v115, v180, s[36:37]
	v_mul_f32_e32 v181, v101, v165
	s_add_u32 s36, s34, 0x6c000
	s_addc_u32 s37, s35, 0
	global_store_dword v115, v181, s[36:37]
	v_mul_f32_e32 v182, v102, v166
	s_add_u32 s36, s34, 0x78000
	s_addc_u32 s37, s35, 0
	global_store_dword v115, v182, s[36:37]
	v_mul_f32_e32 v183, v103, v167
	s_add_u32 s36, s34, 0x84000
	s_addc_u32 s37, s35, 0
	global_store_dword v115, v183, s[36:37]
	v_mul_f32_e32 v184, v104, v168
	s_add_u32 s36, s34, 0xc0000
	s_addc_u32 s37, s35, 0
	global_store_dword v115, v184, s[36:37]
	v_mul_f32_e32 v185, v105, v169
	s_add_u32 s36, s34, 0xcc000
	s_addc_u32 s37, s35, 0
	global_store_dword v115, v185, s[36:37]
	v_mul_f32_e32 v186, v106, v170
	s_add_u32 s36, s34, 0xd8000
	s_addc_u32 s37, s35, 0
	global_store_dword v115, v186, s[36:37]
	v_mul_f32_e32 v187, v107, v171
	s_add_u32 s36, s34, 0xe4000
	s_addc_u32 s37, s35, 0
	global_store_dword v115, v187, s[36:37]
	v_mul_f32_e32 v188, v108, v172
	s_add_u32 s36, s34, 0x120000
	s_addc_u32 s37, s35, 0
	global_store_dword v115, v188, s[36:37]
	v_mul_f32_e32 v189, v109, v173
	s_add_u32 s36, s34, 0x12c000
	s_addc_u32 s37, s35, 0
	global_store_dword v115, v189, s[36:37]
	v_mul_f32_e32 v190, v110, v174
	s_add_u32 s36, s34, 0x138000
	s_addc_u32 s37, s35, 0
	global_store_dword v115, v190, s[36:37]
	v_mul_f32_e32 v191, v111, v175
	s_add_u32 s36, s34, 0x144000
	s_addc_u32 s37, s35, 0
	global_store_dword v115, v191, s[36:37]
